# P5 + P6 epilogues: first batch of gate/TMP loads prefetched in the unit's last K-trip (counted waits), epilogue waits only for them
# speedup vs baseline: 1.0099x; 1.0099x over previous
.LBB0_771:
	ds_read_b128 v[130:133], v180
	ds_read_b128 v[134:137], v180 offset:1024
	ds_read_b128 v[138:141], v180 offset:2048
	ds_read_b128 v[142:145], v180 offset:3072
	ds_read_b128 v[146:149], v181
	ds_read_b128 v[166:169], v181 offset:1024
	ds_read_b128 v[170:173], v181 offset:2048
	ds_read_b128 v[174:177], v181 offset:3072
	s_add_u32 s36, s0, 0xfffc0080
	s_addc_u32 s37, s1, -1
	s_cmp_eq_u32 s58, 12
	s_cselect_b32 s39, s27, s37
	s_cselect_b32 s38, s54, s36
	s_cselect_b32 s37, s25, s57
	s_cselect_b32 s36, s55, s56
	v_lshl_add_u64 v[216:217], s[0:1], 0, v[158:159]
	s_add_i32 m0, s35, 0xc000
	ds_read_b128 v[184:187], v182
	ds_read_b128 v[188:191], v182 offset:1024
	ds_read_b128 v[192:195], v182 offset:2048
	ds_read_b128 v[196:199], v182 offset:3072
	ds_read_b128 v[200:203], v182 offset:4096
	ds_read_b128 v[204:207], v182 offset:5120
	ds_read_b128 v[208:211], v182 offset:6144
	ds_read_b128 v[212:215], v182 offset:7168
	global_load_lds_dwordx4 v[216:217], off
	v_lshl_add_u64 v[216:217], s[0:1], 0, v[160:161]
	s_add_i32 m0, s35, 0xe000
	s_nop 0
	global_load_lds_dwordx4 v[216:217], off
	s_waitcnt vmcnt(8)
	s_waitcnt lgkmcnt(0)
	s_barrier
	s_setprio 1
	s_waitcnt lgkmcnt(0)
	v_mfma_f32_16x16x32_bf16 v[126:129], v[130:133], v[184:187], v[126:129]
	v_mfma_f32_16x16x32_bf16 v[122:125], v[138:141], v[184:187], v[122:125]
	v_mfma_f32_16x16x32_bf16 v[110:113], v[130:133], v[192:195], v[110:113]
	v_mfma_f32_16x16x32_bf16 v[106:109], v[138:141], v[192:195], v[106:109]
	v_mfma_f32_16x16x32_bf16 v[94:97], v[130:133], v[200:203], v[94:97]
	v_mfma_f32_16x16x32_bf16 v[90:93], v[138:141], v[200:203], v[90:93]
	v_mfma_f32_16x16x32_bf16 v[78:81], v[130:133], v[208:211], v[78:81]
	v_mfma_f32_16x16x32_bf16 v[74:77], v[138:141], v[208:211], v[74:77]
	v_mfma_f32_16x16x32_bf16 v[126:129], v[134:137], v[188:191], v[126:129]
	v_mfma_f32_16x16x32_bf16 v[122:125], v[142:145], v[188:191], v[122:125]
	v_mfma_f32_16x16x32_bf16 v[110:113], v[134:137], v[196:199], v[110:113]
	v_mfma_f32_16x16x32_bf16 v[106:109], v[142:145], v[196:199], v[106:109]
	v_mfma_f32_16x16x32_bf16 v[94:97], v[134:137], v[204:207], v[94:97]
	v_mfma_f32_16x16x32_bf16 v[90:93], v[142:145], v[204:207], v[90:93]
	v_mfma_f32_16x16x32_bf16 v[78:81], v[134:137], v[212:215], v[78:81]
	v_mfma_f32_16x16x32_bf16 v[74:77], v[142:145], v[212:215], v[74:77]
	s_setprio 0
	s_setprio 1
	v_mfma_f32_16x16x32_bf16 v[118:121], v[146:149], v[184:187], v[118:121]
	v_mfma_f32_16x16x32_bf16 v[114:117], v[170:173], v[184:187], v[114:117]
	v_mfma_f32_16x16x32_bf16 v[102:105], v[146:149], v[192:195], v[102:105]
	v_mfma_f32_16x16x32_bf16 v[98:101], v[170:173], v[192:195], v[98:101]
	v_mfma_f32_16x16x32_bf16 v[86:89], v[146:149], v[200:203], v[86:89]
	v_mfma_f32_16x16x32_bf16 v[82:85], v[170:173], v[200:203], v[82:85]
	v_mfma_f32_16x16x32_bf16 v[70:73], v[146:149], v[208:211], v[70:73]
	v_mfma_f32_16x16x32_bf16 v[66:69], v[170:173], v[208:211], v[66:69]
	v_mfma_f32_16x16x32_bf16 v[118:121], v[166:169], v[188:191], v[118:121]
	v_mfma_f32_16x16x32_bf16 v[114:117], v[174:177], v[188:191], v[114:117]
	v_mfma_f32_16x16x32_bf16 v[102:105], v[166:169], v[196:199], v[102:105]
	v_mfma_f32_16x16x32_bf16 v[98:101], v[174:177], v[196:199], v[98:101]
	v_mfma_f32_16x16x32_bf16 v[86:89], v[166:169], v[204:207], v[86:89]
	v_mfma_f32_16x16x32_bf16 v[82:85], v[174:177], v[204:207], v[82:85]
	v_mfma_f32_16x16x32_bf16 v[70:73], v[166:169], v[212:215], v[70:73]
	v_mfma_f32_16x16x32_bf16 v[66:69], v[174:177], v[212:215], v[66:69]
	s_setprio 0
	s_barrier
	s_add_i32 s59, s51, s43
	v_lshl_add_u64 v[216:217], s[36:37], 0, v[152:153]
	s_mov_b32 m0, s59
	ds_read_b128 v[184:187], v182 offset:16384
	ds_read_b128 v[188:191], v182 offset:17408
	ds_read_b128 v[192:195], v182 offset:18432
	ds_read_b128 v[196:199], v182 offset:19456
	ds_read_b128 v[200:203], v182 offset:20480
	ds_read_b128 v[204:207], v182 offset:21504
	ds_read_b128 v[208:211], v182 offset:22528
	ds_read_b128 v[212:215], v182 offset:23552
	global_load_lds_dwordx4 v[216:217], off
	s_add_i32 m0, s59, 0x2000
	s_add_u32 s60, s36, 0x40000
	v_lshl_add_u64 v[218:219], s[36:37], 0, v[156:157]
	s_addc_u32 s61, s37, 0
	s_add_i32 s59, s52, s43
	global_load_lds_dwordx4 v[218:219], off
	v_lshl_add_u64 v[220:221], s[60:61], 0, v[152:153]
	s_mov_b32 m0, s59
	v_lshl_add_u64 v[222:223], s[38:39], 0, v[154:155]
	global_load_lds_dwordx4 v[220:221], off
	v_lshl_add_u64 v[220:221], s[60:61], 0, v[156:157]
	s_add_i32 m0, s59, 0x2000
	s_nop 0
	global_load_lds_dwordx4 v[220:221], off
	v_lshl_add_u64 v[220:221], s[38:39], 0, v[150:151]
	s_mov_b32 m0, s35
	s_nop 0
	global_load_lds_dwordx4 v[220:221], off
	s_mov_b32 m0, s44
	s_nop 0
	global_load_lds_dwordx4 v[222:223], off
	s_waitcnt vmcnt(8)
	s_waitcnt lgkmcnt(0)
	s_barrier
	s_setprio 1
	s_waitcnt lgkmcnt(0)
	v_mfma_f32_16x16x32_bf16 v[6:9], v[130:133], v[184:187], v[6:9]
	v_mfma_f32_16x16x32_bf16 v[2:5], v[138:141], v[184:187], v[2:5]
	v_mfma_f32_16x16x32_bf16 v[22:25], v[130:133], v[192:195], v[22:25]
	v_mfma_f32_16x16x32_bf16 v[18:21], v[138:141], v[192:195], v[18:21]
	v_mfma_f32_16x16x32_bf16 v[38:41], v[130:133], v[200:203], v[38:41]
	v_mfma_f32_16x16x32_bf16 v[34:37], v[138:141], v[200:203], v[34:37]
	v_mfma_f32_16x16x32_bf16 v[54:57], v[130:133], v[208:211], v[54:57]
	v_mfma_f32_16x16x32_bf16 v[50:53], v[138:141], v[208:211], v[50:53]
	v_mfma_f32_16x16x32_bf16 v[6:9], v[134:137], v[188:191], v[6:9]
	v_mfma_f32_16x16x32_bf16 v[2:5], v[142:145], v[188:191], v[2:5]
	v_mfma_f32_16x16x32_bf16 v[22:25], v[134:137], v[196:199], v[22:25]
	v_mfma_f32_16x16x32_bf16 v[18:21], v[142:145], v[196:199], v[18:21]
	v_mfma_f32_16x16x32_bf16 v[38:41], v[134:137], v[204:207], v[38:41]
	v_mfma_f32_16x16x32_bf16 v[34:37], v[142:145], v[204:207], v[34:37]
	v_mfma_f32_16x16x32_bf16 v[54:57], v[134:137], v[212:215], v[54:57]
	v_mfma_f32_16x16x32_bf16 v[50:53], v[142:145], v[212:215], v[50:53]
	s_setprio 0
	s_setprio 1
	v_mfma_f32_16x16x32_bf16 v[14:17], v[146:149], v[184:187], v[14:17]
	v_mfma_f32_16x16x32_bf16 v[10:13], v[170:173], v[184:187], v[10:13]
	v_mfma_f32_16x16x32_bf16 v[30:33], v[146:149], v[192:195], v[30:33]
	v_mfma_f32_16x16x32_bf16 v[26:29], v[170:173], v[192:195], v[26:29]
	v_mfma_f32_16x16x32_bf16 v[46:49], v[146:149], v[200:203], v[46:49]
	v_mfma_f32_16x16x32_bf16 v[42:45], v[170:173], v[200:203], v[42:45]
	v_mfma_f32_16x16x32_bf16 v[62:65], v[146:149], v[208:211], v[62:65]
	v_mfma_f32_16x16x32_bf16 v[58:61], v[170:173], v[208:211], v[58:61]
	v_mfma_f32_16x16x32_bf16 v[14:17], v[166:169], v[188:191], v[14:17]
	v_mfma_f32_16x16x32_bf16 v[10:13], v[174:177], v[188:191], v[10:13]
	v_mfma_f32_16x16x32_bf16 v[30:33], v[166:169], v[196:199], v[30:33]
	v_mfma_f32_16x16x32_bf16 v[26:29], v[174:177], v[196:199], v[26:29]
	v_mfma_f32_16x16x32_bf16 v[46:49], v[166:169], v[204:207], v[46:49]
	v_mfma_f32_16x16x32_bf16 v[42:45], v[174:177], v[204:207], v[42:45]
	v_mfma_f32_16x16x32_bf16 v[62:65], v[166:169], v[212:215], v[62:65]
	v_mfma_f32_16x16x32_bf16 v[58:61], v[174:177], v[212:215], v[58:61]
	s_setprio 0
	s_barrier
	s_cmp_lg_u32 s58, 12
	s_cbranch_scc1 .Lmy_p5_nox
	v_lshl_or_b32 v183, s53, 8, v179
	v_lshl_add_u32 v226, s34, 8, v1
	v_lshlrev_b32_e32 v183, 1, v183
	v_lshl_add_u32 v183, v226, 11, v183
	global_load_dwordx4 v[226:229], v183, s[12:13]
	global_load_dwordx4 v[230:233], v183, s[12:13] offset:256
	v_add_u32_e32 v183, 0x8000, v183
	global_load_dwordx4 v[234:237], v183, s[12:13]
	global_load_dwordx4 v[238:241], v183, s[12:13] offset:256
	v_add_u32_e32 v183, 0x8000, v183
	global_load_dwordx4 v[242:245], v183, s[12:13]
	global_load_dwordx4 v[246:249], v183, s[12:13] offset:256
	v_add_u32_e32 v183, 0x8000, v183
	global_load_dwordx4 v[250:253], v183, s[12:13]
	global_load_dwordx4 v[162:165], v183, s[12:13] offset:256
.Lmy_p5_nox:
	s_add_i32 s59, 0, 0x18000
	s_add_i32 s60, 0, 0x1c000
	v_add_u32_e32 v142, s59, v178
	v_add_u32_e32 v174, s60, v178
	ds_read_b128 v[130:133], v142
	ds_read_b128 v[134:137], v142 offset:1024
	ds_read_b128 v[138:141], v142 offset:2048
	ds_read_b128 v[142:145], v142 offset:3072
	ds_read_b128 v[146:149], v174
	ds_read_b128 v[166:169], v174 offset:1024
	ds_read_b128 v[170:173], v174 offset:2048
	ds_read_b128 v[174:177], v174 offset:3072
	s_add_u32 s38, s38, 0x40000
	s_addc_u32 s39, s39, 0
	s_mov_b32 m0, s45
	v_lshl_add_u64 v[224:225], s[38:39], 0, v[150:151]
	ds_read_b128 v[184:187], v182 offset:32768
	ds_read_b128 v[188:191], v182 offset:33792
	ds_read_b128 v[192:195], v182 offset:34816
	ds_read_b128 v[196:199], v182 offset:35840
	ds_read_b128 v[200:203], v182 offset:36864
	ds_read_b128 v[204:207], v182 offset:37888
	ds_read_b128 v[208:211], v182 offset:38912
	ds_read_b128 v[212:215], v182 offset:39936
	global_load_lds_dwordx4 v[224:225], off
	v_lshl_add_u64 v[224:225], s[38:39], 0, v[154:155]
	s_mov_b32 m0, s46
	s_nop 0
	global_load_lds_dwordx4 v[224:225], off
	s_cmp_eq_u32 s58, 12
	s_cbranch_scc1 .Lmy_p5_wc_last
	s_waitcnt vmcnt(8)
	s_branch .Lmy_p5_wc_done
.Lmy_p5_wc_last:
	s_waitcnt vmcnt(16)
.Lmy_p5_wc_done:
	s_waitcnt lgkmcnt(0)
	s_barrier
	s_setprio 1
	s_waitcnt lgkmcnt(0)
	v_mfma_f32_16x16x32_bf16 v[126:129], v[130:133], v[184:187], v[126:129]
	v_mfma_f32_16x16x32_bf16 v[122:125], v[138:141], v[184:187], v[122:125]
	v_mfma_f32_16x16x32_bf16 v[110:113], v[130:133], v[192:195], v[110:113]
	v_mfma_f32_16x16x32_bf16 v[106:109], v[138:141], v[192:195], v[106:109]
	v_mfma_f32_16x16x32_bf16 v[94:97], v[130:133], v[200:203], v[94:97]
	v_mfma_f32_16x16x32_bf16 v[90:93], v[138:141], v[200:203], v[90:93]
	v_mfma_f32_16x16x32_bf16 v[78:81], v[130:133], v[208:211], v[78:81]
	v_mfma_f32_16x16x32_bf16 v[74:77], v[138:141], v[208:211], v[74:77]
	v_mfma_f32_16x16x32_bf16 v[126:129], v[134:137], v[188:191], v[126:129]
	v_mfma_f32_16x16x32_bf16 v[122:125], v[142:145], v[188:191], v[122:125]
	v_mfma_f32_16x16x32_bf16 v[110:113], v[134:137], v[196:199], v[110:113]
	v_mfma_f32_16x16x32_bf16 v[106:109], v[142:145], v[196:199], v[106:109]
	v_mfma_f32_16x16x32_bf16 v[94:97], v[134:137], v[204:207], v[94:97]
	v_mfma_f32_16x16x32_bf16 v[90:93], v[142:145], v[204:207], v[90:93]
	v_mfma_f32_16x16x32_bf16 v[78:81], v[134:137], v[212:215], v[78:81]
	v_mfma_f32_16x16x32_bf16 v[74:77], v[142:145], v[212:215], v[74:77]
	s_setprio 0
	s_setprio 1
	v_mfma_f32_16x16x32_bf16 v[118:121], v[146:149], v[184:187], v[118:121]
	v_mfma_f32_16x16x32_bf16 v[114:117], v[170:173], v[184:187], v[114:117]
	v_mfma_f32_16x16x32_bf16 v[102:105], v[146:149], v[192:195], v[102:105]
	v_mfma_f32_16x16x32_bf16 v[98:101], v[170:173], v[192:195], v[98:101]
	v_mfma_f32_16x16x32_bf16 v[86:89], v[146:149], v[200:203], v[86:89]
	v_mfma_f32_16x16x32_bf16 v[82:85], v[170:173], v[200:203], v[82:85]
	v_mfma_f32_16x16x32_bf16 v[70:73], v[146:149], v[208:211], v[70:73]
	v_mfma_f32_16x16x32_bf16 v[66:69], v[170:173], v[208:211], v[66:69]
	v_mfma_f32_16x16x32_bf16 v[118:121], v[166:169], v[188:191], v[118:121]
	v_mfma_f32_16x16x32_bf16 v[114:117], v[174:177], v[188:191], v[114:117]
	v_mfma_f32_16x16x32_bf16 v[102:105], v[166:169], v[196:199], v[102:105]
	v_mfma_f32_16x16x32_bf16 v[98:101], v[174:177], v[196:199], v[98:101]
	v_mfma_f32_16x16x32_bf16 v[86:89], v[166:169], v[204:207], v[86:89]
	v_mfma_f32_16x16x32_bf16 v[82:85], v[174:177], v[204:207], v[82:85]
	v_mfma_f32_16x16x32_bf16 v[70:73], v[166:169], v[212:215], v[70:73]
	v_mfma_f32_16x16x32_bf16 v[66:69], v[174:177], v[212:215], v[66:69]
	s_setprio 0
	s_barrier
	s_add_i32 s38, s59, s43
	v_lshl_add_u64 v[216:217], v[216:217], 0, s[14:15]
	s_mov_b32 m0, s38
	ds_read_b128 v[184:187], v182 offset:49152
	ds_read_b128 v[188:191], v182 offset:50176
	ds_read_b128 v[192:195], v182 offset:51200
	ds_read_b128 v[196:199], v182 offset:52224
	ds_read_b128 v[200:203], v182 offset:53248
	ds_read_b128 v[204:207], v182 offset:54272
	ds_read_b128 v[208:211], v182 offset:55296
	ds_read_b128 v[212:215], v182 offset:56320
	global_load_lds_dwordx4 v[216:217], off
	s_add_i32 m0, s38, 0x2000
	s_add_u32 s36, s36, 0x40080
	v_lshl_add_u64 v[216:217], v[218:219], 0, s[14:15]
	s_addc_u32 s37, s37, 0
	s_add_i32 s38, s60, s43
	global_load_lds_dwordx4 v[216:217], off
	v_lshl_add_u64 v[216:217], s[36:37], 0, v[152:153]
	s_mov_b32 m0, s38
	s_nop 0
	global_load_lds_dwordx4 v[216:217], off
	v_lshl_add_u64 v[216:217], s[36:37], 0, v[156:157]
	s_add_i32 m0, s38, 0x2000
	s_nop 0
	global_load_lds_dwordx4 v[216:217], off
	v_lshl_add_u64 v[216:217], v[220:221], 0, s[14:15]
	s_mov_b32 m0, s48
	s_nop 0
	global_load_lds_dwordx4 v[216:217], off
	v_lshl_add_u64 v[216:217], v[222:223], 0, s[14:15]
	s_mov_b32 m0, s49
	s_nop 0
	global_load_lds_dwordx4 v[216:217], off
	s_cmp_eq_u32 s58, 12
	s_cbranch_scc1 .Lmy_p5_wd_last
	s_waitcnt vmcnt(8)
	s_branch .Lmy_p5_wd_done

.Lmy_p5_wd_done:
	s_waitcnt lgkmcnt(0)
	s_barrier
	s_setprio 1
	s_waitcnt lgkmcnt(0)
	v_mfma_f32_16x16x32_bf16 v[6:9], v[130:133], v[184:187], v[6:9]
	v_mfma_f32_16x16x32_bf16 v[2:5], v[138:141], v[184:187], v[2:5]
	v_mfma_f32_16x16x32_bf16 v[22:25], v[130:133], v[192:195], v[22:25]
	v_mfma_f32_16x16x32_bf16 v[18:21], v[138:141], v[192:195], v[18:21]
	v_mfma_f32_16x16x32_bf16 v[38:41], v[130:133], v[200:203], v[38:41]
	v_mfma_f32_16x16x32_bf16 v[34:37], v[138:141], v[200:203], v[34:37]
	v_mfma_f32_16x16x32_bf16 v[54:57], v[130:133], v[208:211], v[54:57]
	v_mfma_f32_16x16x32_bf16 v[50:53], v[138:141], v[208:211], v[50:53]
	v_mfma_f32_16x16x32_bf16 v[6:9], v[134:137], v[188:191], v[6:9]
	v_mfma_f32_16x16x32_bf16 v[2:5], v[142:145], v[188:191], v[2:5]
	v_mfma_f32_16x16x32_bf16 v[22:25], v[134:137], v[196:199], v[22:25]
	v_mfma_f32_16x16x32_bf16 v[18:21], v[142:145], v[196:199], v[18:21]
	v_mfma_f32_16x16x32_bf16 v[38:41], v[134:137], v[204:207], v[38:41]
	v_mfma_f32_16x16x32_bf16 v[34:37], v[142:145], v[204:207], v[34:37]
	v_mfma_f32_16x16x32_bf16 v[54:57], v[134:137], v[212:215], v[54:57]
	v_mfma_f32_16x16x32_bf16 v[50:53], v[142:145], v[212:215], v[50:53]
	s_setprio 0
	s_setprio 1
	v_mfma_f32_16x16x32_bf16 v[14:17], v[146:149], v[184:187], v[14:17]
	v_mfma_f32_16x16x32_bf16 v[10:13], v[170:173], v[184:187], v[10:13]
	v_mfma_f32_16x16x32_bf16 v[30:33], v[146:149], v[192:195], v[30:33]
	v_mfma_f32_16x16x32_bf16 v[26:29], v[170:173], v[192:195], v[26:29]
	v_mfma_f32_16x16x32_bf16 v[46:49], v[146:149], v[200:203], v[46:49]
	v_mfma_f32_16x16x32_bf16 v[42:45], v[170:173], v[200:203], v[42:45]
	v_mfma_f32_16x16x32_bf16 v[62:65], v[146:149], v[208:211], v[62:65]
	v_mfma_f32_16x16x32_bf16 v[58:61], v[170:173], v[208:211], v[58:61]
	v_mfma_f32_16x16x32_bf16 v[14:17], v[166:169], v[188:191], v[14:17]
	v_mfma_f32_16x16x32_bf16 v[10:13], v[174:177], v[188:191], v[10:13]
	v_mfma_f32_16x16x32_bf16 v[30:33], v[166:169], v[196:199], v[30:33]
	v_mfma_f32_16x16x32_bf16 v[26:29], v[174:177], v[196:199], v[26:29]
	v_mfma_f32_16x16x32_bf16 v[46:49], v[166:169], v[204:207], v[46:49]
	v_mfma_f32_16x16x32_bf16 v[42:45], v[174:177], v[204:207], v[42:45]
	v_mfma_f32_16x16x32_bf16 v[62:65], v[166:169], v[212:215], v[62:65]
	v_mfma_f32_16x16x32_bf16 v[58:61], v[174:177], v[212:215], v[58:61]
	s_setprio 0
	s_barrier
	s_add_i32 s58, s58, 2
	s_add_u32 s0, s0, 0x100
	s_addc_u32 s1, s1, 0
	s_add_u32 s56, s56, 0x100
	s_addc_u32 s57, s57, 0
	s_cmp_gt_u32 s58, 13
	s_cbranch_scc0 .LBB0_771
	s_and_b64 vcc, exec, s[16:17]
	s_cbranch_vccz .LBB0_774
	s_barrier
.LBB0_774:
	v_lshl_or_b32 v132, s53, 8, v179
	v_lshl_add_u32 v130, s34, 8, v1
	v_ashrrev_i32_e32 v133, 31, v132
	v_lshlrev_b64 v[166:167], 1, v[132:133]
	v_ashrrev_i32_e32 v131, 31, v130
	v_lshl_add_u64 v[168:169], s[12:13], 0, v[166:167]
	v_lshlrev_b64 v[170:171], 11, v[130:131]
	v_lshl_add_u64 v[132:133], v[168:169], 0, v[170:171]
	s_waitcnt vmcnt(8)
	v_mov_b32_e32 v184, v226
	v_mov_b32_e32 v185, v227
	v_mov_b32_e32 v186, v228
	v_mov_b32_e32 v187, v229
	v_mov_b32_e32 v188, v230
	v_mov_b32_e32 v189, v231
	v_mov_b32_e32 v190, v232
	v_mov_b32_e32 v191, v233
	v_or_b32_e32 v132, 16, v130
	v_or_b32_e32 v134, 32, v130
	v_or_b32_e32 v130, 48, v130
	v_ashrrev_i32_e32 v133, 31, v132
	v_ashrrev_i32_e32 v135, 31, v134
	v_ashrrev_i32_e32 v131, 31, v130
	v_lshlrev_b64 v[176:177], 11, v[132:133]
	v_lshlrev_b64 v[174:175], 11, v[134:135]
	v_lshlrev_b64 v[172:173], 11, v[130:131]
	v_lshl_add_u64 v[130:131], v[168:169], 0, v[176:177]
	v_lshl_add_u64 v[132:133], v[168:169], 0, v[174:175]
	v_lshl_add_u64 v[196:197], v[168:169], 0, v[172:173]
	v_mov_b32_e32 v192, v234
	v_mov_b32_e32 v193, v235
	v_mov_b32_e32 v194, v236
	v_mov_b32_e32 v195, v237
	v_mov_b32_e32 v146, v238
	v_mov_b32_e32 v147, v239
	v_mov_b32_e32 v148, v240
	v_mov_b32_e32 v149, v241
	v_mov_b32_e32 v142, v242
	v_mov_b32_e32 v143, v243
	v_mov_b32_e32 v144, v244
	v_mov_b32_e32 v145, v245
	v_mov_b32_e32 v138, v246
	v_mov_b32_e32 v139, v247
	v_mov_b32_e32 v140, v248
	v_mov_b32_e32 v141, v249
	v_mov_b32_e32 v134, v250
	v_mov_b32_e32 v135, v251
	v_mov_b32_e32 v136, v252
	v_mov_b32_e32 v137, v253
	s_nop 0
	v_mov_b32_e32 v130, v162
	v_mov_b32_e32 v131, v163
	v_mov_b32_e32 v132, v164
	v_mov_b32_e32 v133, v165
	s_andn2_b64 vcc, exec, s[2:3]
	s_mov_b64 s[0:1], -1
	s_waitcnt vmcnt(8)
	v_lshlrev_b32_e32 v183, 16, v184
	v_and_b32_e32 v184, 0xffff0000, v184
	v_lshlrev_b32_e32 v197, 16, v186
	v_lshlrev_b32_e32 v196, 16, v185
	v_and_b32_e32 v185, 0xffff0000, v185
	v_and_b32_e32 v186, 0xffff0000, v186
	v_lshlrev_b32_e32 v198, 16, v187
	v_and_b32_e32 v187, 0xffff0000, v187
	v_lshlrev_b32_e32 v202, 16, v191
	v_and_b32_e32 v203, 0xffff0000, v191
	v_mul_f32_e32 v183, 0xbfb8aa3b, v183
	v_mul_f32_e32 v191, 0xbfb8aa3b, v197
	v_mul_f32_e32 v184, 0xbfb8aa3b, v184
	v_lshlrev_b32_e32 v199, 16, v188
	v_and_b32_e32 v188, 0xffff0000, v188
	v_lshlrev_b32_e32 v200, 16, v189
	v_and_b32_e32 v201, 0xffff0000, v189
	v_lshlrev_b32_e32 v189, 16, v190
	v_mul_f32_e32 v186, 0xbfb8aa3b, v186
	v_mul_f32_e32 v196, 0xbfb8aa3b, v196
	v_mul_f32_e32 v197, 0xbfb8aa3b, v198
	v_mul_f32_e32 v185, 0xbfb8aa3b, v185
	v_mul_f32_e32 v187, 0xbfb8aa3b, v187
	v_exp_f32_e32 v183, v183
	v_exp_f32_e32 v191, v191
	v_exp_f32_e32 v184, v184
	v_mul_f32_e32 v189, 0xbfb8aa3b, v189
	v_mul_f32_e32 v188, 0xbfb8aa3b, v188
	v_exp_f32_e32 v186, v186
	v_exp_f32_e32 v196, v196
	v_exp_f32_e32 v197, v197
	v_exp_f32_e32 v185, v185
	v_exp_f32_e32 v187, v187
	v_and_b32_e32 v190, 0xffff0000, v190
	v_exp_f32_e32 v189, v189
	v_exp_f32_e32 v188, v188
	v_mul_f32_e32 v190, 0xbfb8aa3b, v190
	v_mul_f32_e32 v198, 0xbfb8aa3b, v199
	v_exp_f32_e32 v199, v190
	v_add_f32_e32 v183, 1.0, v183
	v_add_f32_e32 v190, 1.0, v191
	v_add_f32_e32 v191, 1.0, v184
	v_add_f32_e32 v204, 1.0, v186
	v_add_f32_e32 v196, 1.0, v196
	v_add_f32_e32 v197, 1.0, v197
	v_add_f32_e32 v205, 1.0, v185
	v_add_f32_e32 v206, 1.0, v187
	v_rcp_f32_e32 v184, v183
	v_rcp_f32_e32 v185, v191
	v_add_f32_e32 v207, 1.0, v189
	v_add_f32_e32 v208, 1.0, v188
	v_rcp_f32_e32 v186, v190
	v_rcp_f32_e32 v187, v204
	v_rcp_f32_e32 v188, v196
	v_rcp_f32_e32 v190, v197
	v_rcp_f32_e32 v189, v205
	v_rcp_f32_e32 v191, v206
	v_pk_mul_f32 v[126:127], v[126:127], v[184:185]
	v_exp_f32_e32 v198, v198
	v_pk_mul_f32 v[128:129], v[128:129], v[188:189]
	v_pk_mul_f32 v[184:185], v[124:125], v[190:191]
	v_pk_mul_f32 v[124:125], v[122:123], v[186:187]
	v_cvt_pk_bf16_f32 v122, v126, v127
	v_mul_f32_e32 v127, 0xbfb8aa3b, v202
	v_cvt_pk_bf16_f32 v123, v128, v129
	v_mul_f32_e32 v126, 0xbfb8aa3b, v200
	v_exp_f32_e32 v127, v127
	v_mul_f32_e32 v128, 0xbfb8aa3b, v201
	v_exp_f32_e32 v126, v126
	v_exp_f32_e32 v129, v128
	v_mul_f32_e32 v128, 0xbfb8aa3b, v203
	v_cvt_pk_bf16_f32 v124, v124, v125
	v_cvt_pk_bf16_f32 v125, v184, v185
	v_exp_f32_e32 v184, v128
	v_add_f32_e32 v127, 1.0, v127
	v_add_f32_e32 v126, 1.0, v126
	v_rcp_f32_e32 v128, v127
	v_add_f32_e32 v127, 1.0, v129
	v_add_f32_e32 v198, 1.0, v198
	v_add_f32_e32 v183, 1.0, v199
	v_rcp_f32_e32 v126, v126
	v_rcp_f32_e32 v127, v127
	v_add_f32_e32 v129, 1.0, v184
	v_rcp_f32_e32 v196, v198
	v_rcp_f32_e32 v198, v207
	v_rcp_f32_e32 v129, v129
	v_rcp_f32_e32 v199, v183
	v_pk_mul_f32 v[120:121], v[120:121], v[126:127]
	v_rcp_f32_e32 v197, v208
	v_pk_mul_f32 v[126:127], v[116:117], v[128:129]
	v_pk_mul_f32 v[116:117], v[114:115], v[198:199]
	v_cvt_pk_bf16_f32 v115, v120, v121
	v_lshlrev_b32_e32 v121, 16, v193
	v_cvt_pk_bf16_f32 v116, v116, v117
	v_cvt_pk_bf16_f32 v117, v126, v127
	v_and_b32_e32 v126, 0xffff0000, v194
	v_lshlrev_b32_e32 v128, 16, v195
	v_mul_f32_e32 v121, 0xbfb8aa3b, v121
	v_mul_f32_e32 v126, 0xbfb8aa3b, v126
	v_exp_f32_e32 v121, v121
	v_mul_f32_e32 v128, 0xbfb8aa3b, v128
	v_exp_f32_e32 v126, v126
	v_exp_f32_e32 v128, v128
	v_pk_mul_f32 v[118:119], v[118:119], v[196:197]
	v_and_b32_e32 v127, 0xffff0000, v193
	v_cvt_pk_bf16_f32 v114, v118, v119
	v_lshlrev_b32_e32 v118, 16, v192
	v_and_b32_e32 v119, 0xffff0000, v192
	v_lshlrev_b32_e32 v120, 16, v194
	v_and_b32_e32 v129, 0xffff0000, v195
	v_add_f32_e32 v121, 1.0, v121
	v_mul_f32_e32 v127, 0xbfb8aa3b, v127
	v_mul_f32_e32 v118, 0xbfb8aa3b, v118
	v_mul_f32_e32 v120, 0xbfb8aa3b, v120
	v_mul_f32_e32 v119, 0xbfb8aa3b, v119
	v_add_f32_e32 v183, 1.0, v126
	v_rcp_f32_e32 v126, v121
	v_add_f32_e32 v121, 1.0, v128
	v_exp_f32_e32 v127, v127
	v_mul_f32_e32 v128, 0xbfb8aa3b, v129
	v_exp_f32_e32 v118, v118
	v_exp_f32_e32 v120, v120
	v_exp_f32_e32 v119, v119
	v_exp_f32_e32 v129, v128
	v_rcp_f32_e32 v128, v121
	v_add_f32_e32 v121, 1.0, v127
	v_add_f32_e32 v118, 1.0, v118
	v_add_f32_e32 v120, 1.0, v120
	v_add_f32_e32 v119, 1.0, v119
	v_rcp_f32_e32 v127, v121
	v_add_f32_e32 v121, 1.0, v129
	v_rcp_f32_e32 v118, v118
	v_rcp_f32_e32 v120, v120
	v_rcp_f32_e32 v119, v119
	v_rcp_f32_e32 v129, v121
	v_rcp_f32_e32 v121, v183
	v_pk_mul_f32 v[112:113], v[112:113], v[126:127]
	v_pk_mul_f32 v[110:111], v[110:111], v[118:119]
	v_pk_mul_f32 v[118:119], v[108:109], v[128:129]
	v_pk_mul_f32 v[108:109], v[106:107], v[120:121]
	v_cvt_pk_bf16_f32 v107, v112, v113
	v_lshlrev_b32_e32 v113, 16, v147
	v_cvt_pk_bf16_f32 v108, v108, v109
	v_cvt_pk_bf16_f32 v109, v118, v119
	v_and_b32_e32 v118, 0xffff0000, v148
	v_lshlrev_b32_e32 v120, 16, v149
	v_mul_f32_e32 v113, 0xbfb8aa3b, v113
	v_mul_f32_e32 v118, 0xbfb8aa3b, v118
	v_exp_f32_e32 v113, v113
	v_mul_f32_e32 v120, 0xbfb8aa3b, v120
	v_exp_f32_e32 v118, v118
	v_exp_f32_e32 v120, v120
	v_and_b32_e32 v119, 0xffff0000, v147
	v_cvt_pk_bf16_f32 v106, v110, v111
	v_lshlrev_b32_e32 v110, 16, v146
	v_and_b32_e32 v111, 0xffff0000, v146
	v_lshlrev_b32_e32 v112, 16, v148
	v_and_b32_e32 v121, 0xffff0000, v149
	v_add_f32_e32 v113, 1.0, v113
	v_mul_f32_e32 v119, 0xbfb8aa3b, v119
	v_mul_f32_e32 v110, 0xbfb8aa3b, v110
	v_mul_f32_e32 v112, 0xbfb8aa3b, v112
	v_mul_f32_e32 v111, 0xbfb8aa3b, v111
	v_add_f32_e32 v126, 1.0, v118
	v_rcp_f32_e32 v118, v113
	v_add_f32_e32 v113, 1.0, v120
	v_exp_f32_e32 v119, v119
	v_mul_f32_e32 v120, 0xbfb8aa3b, v121
	v_exp_f32_e32 v110, v110
	v_exp_f32_e32 v112, v112
	v_exp_f32_e32 v111, v111
	v_exp_f32_e32 v121, v120
	v_rcp_f32_e32 v120, v113
	v_add_f32_e32 v113, 1.0, v119
	v_add_f32_e32 v110, 1.0, v110
	v_add_f32_e32 v112, 1.0, v112
	v_add_f32_e32 v111, 1.0, v111
	v_rcp_f32_e32 v119, v113
	v_add_f32_e32 v113, 1.0, v121
	v_rcp_f32_e32 v110, v110
	v_rcp_f32_e32 v112, v112
	v_rcp_f32_e32 v111, v111
	v_rcp_f32_e32 v121, v113
	v_rcp_f32_e32 v113, v126
	v_pk_mul_f32 v[104:105], v[104:105], v[118:119]
	v_pk_mul_f32 v[102:103], v[102:103], v[110:111]
	v_pk_mul_f32 v[110:111], v[100:101], v[120:121]
	v_pk_mul_f32 v[100:101], v[98:99], v[112:113]
	v_cvt_pk_bf16_f32 v99, v104, v105
	v_lshlrev_b32_e32 v105, 16, v143
	v_cvt_pk_bf16_f32 v100, v100, v101
	v_cvt_pk_bf16_f32 v101, v110, v111
	v_and_b32_e32 v110, 0xffff0000, v144
	v_lshlrev_b32_e32 v112, 16, v145
	v_mul_f32_e32 v105, 0xbfb8aa3b, v105
	v_mul_f32_e32 v110, 0xbfb8aa3b, v110
	v_exp_f32_e32 v105, v105
	v_mul_f32_e32 v112, 0xbfb8aa3b, v112
	v_exp_f32_e32 v110, v110
	v_exp_f32_e32 v112, v112
	v_and_b32_e32 v111, 0xffff0000, v143
	v_cvt_pk_bf16_f32 v98, v102, v103
	v_lshlrev_b32_e32 v102, 16, v142
	v_and_b32_e32 v103, 0xffff0000, v142
	v_lshlrev_b32_e32 v104, 16, v144
	v_and_b32_e32 v113, 0xffff0000, v145
	v_add_f32_e32 v105, 1.0, v105
	v_mul_f32_e32 v111, 0xbfb8aa3b, v111
	v_mul_f32_e32 v102, 0xbfb8aa3b, v102
	v_mul_f32_e32 v104, 0xbfb8aa3b, v104
	v_mul_f32_e32 v103, 0xbfb8aa3b, v103
	v_add_f32_e32 v118, 1.0, v110
	v_rcp_f32_e32 v110, v105
	v_add_f32_e32 v105, 1.0, v112
	v_exp_f32_e32 v111, v111
	v_mul_f32_e32 v112, 0xbfb8aa3b, v113
	v_exp_f32_e32 v102, v102
	v_exp_f32_e32 v104, v104
	v_exp_f32_e32 v103, v103
	v_exp_f32_e32 v113, v112
	v_rcp_f32_e32 v112, v105
	v_add_f32_e32 v105, 1.0, v111
	v_add_f32_e32 v102, 1.0, v102
	v_add_f32_e32 v104, 1.0, v104
	v_add_f32_e32 v103, 1.0, v103
	v_rcp_f32_e32 v111, v105
	v_add_f32_e32 v105, 1.0, v113
	v_rcp_f32_e32 v102, v102
	v_rcp_f32_e32 v104, v104
	v_rcp_f32_e32 v103, v103
	v_rcp_f32_e32 v113, v105
	v_rcp_f32_e32 v105, v118
	v_pk_mul_f32 v[96:97], v[96:97], v[110:111]
	v_pk_mul_f32 v[94:95], v[94:95], v[102:103]
	v_pk_mul_f32 v[102:103], v[92:93], v[112:113]
	v_pk_mul_f32 v[92:93], v[90:91], v[104:105]
	v_cvt_pk_bf16_f32 v91, v96, v97
	v_lshlrev_b32_e32 v97, 16, v139
	v_cvt_pk_bf16_f32 v92, v92, v93
	v_cvt_pk_bf16_f32 v93, v102, v103
	v_and_b32_e32 v102, 0xffff0000, v140
	v_lshlrev_b32_e32 v104, 16, v141
	v_mul_f32_e32 v97, 0xbfb8aa3b, v97
	v_mul_f32_e32 v102, 0xbfb8aa3b, v102
	v_exp_f32_e32 v97, v97
	v_mul_f32_e32 v104, 0xbfb8aa3b, v104
	v_exp_f32_e32 v102, v102
	v_exp_f32_e32 v104, v104
	v_and_b32_e32 v103, 0xffff0000, v139
	v_and_b32_e32 v105, 0xffff0000, v141
	v_add_f32_e32 v97, 1.0, v97
	v_mul_f32_e32 v103, 0xbfb8aa3b, v103
	v_cvt_pk_bf16_f32 v90, v94, v95
	v_lshlrev_b32_e32 v94, 16, v138
	v_and_b32_e32 v95, 0xffff0000, v138
	v_add_f32_e32 v110, 1.0, v102
	v_rcp_f32_e32 v102, v97
	v_add_f32_e32 v97, 1.0, v104
	v_exp_f32_e32 v103, v103
	v_mul_f32_e32 v104, 0xbfb8aa3b, v105
	v_mul_f32_e32 v94, 0xbfb8aa3b, v94
	v_mul_f32_e32 v95, 0xbfb8aa3b, v95
	v_exp_f32_e32 v105, v104
	v_lshlrev_b32_e32 v96, 16, v140
	v_exp_f32_e32 v94, v94
	v_exp_f32_e32 v95, v95
	v_mul_f32_e32 v96, 0xbfb8aa3b, v96
	v_exp_f32_e32 v96, v96
	v_rcp_f32_e32 v104, v97
	v_add_f32_e32 v97, 1.0, v103
	v_rcp_f32_e32 v103, v97
	v_add_f32_e32 v97, 1.0, v105
	v_add_f32_e32 v94, 1.0, v94
	v_add_f32_e32 v95, 1.0, v95
	v_rcp_f32_e32 v105, v97
	v_rcp_f32_e32 v94, v94
	v_rcp_f32_e32 v95, v95
	v_add_f32_e32 v96, 1.0, v96
	v_rcp_f32_e32 v96, v96
	v_rcp_f32_e32 v97, v110
	v_pk_mul_f32 v[84:85], v[84:85], v[104:105]
	v_pk_mul_f32 v[88:89], v[88:89], v[102:103]
	v_pk_mul_f32 v[86:87], v[86:87], v[94:95]
	v_cvt_pk_bf16_f32 v105, v84, v85
	v_lshlrev_b32_e32 v85, 16, v135
	v_cvt_pk_bf16_f32 v102, v86, v87
	v_cvt_pk_bf16_f32 v103, v88, v89
	v_and_b32_e32 v86, 0xffff0000, v136
	v_lshlrev_b32_e32 v88, 16, v137
	v_mul_f32_e32 v85, 0xbfb8aa3b, v85
	v_pk_mul_f32 v[82:83], v[82:83], v[96:97]
	v_and_b32_e32 v87, 0xffff0000, v135
	v_mul_f32_e32 v86, 0xbfb8aa3b, v86
	v_exp_f32_e32 v85, v85
	v_mul_f32_e32 v88, 0xbfb8aa3b, v88
	v_cvt_pk_bf16_f32 v104, v82, v83
	v_lshlrev_b32_e32 v82, 16, v134
	v_and_b32_e32 v83, 0xffff0000, v134
	v_exp_f32_e32 v86, v86
	v_exp_f32_e32 v88, v88
	v_mul_f32_e32 v87, 0xbfb8aa3b, v87
	v_mul_f32_e32 v82, 0xbfb8aa3b, v82
	v_mul_f32_e32 v83, 0xbfb8aa3b, v83
	v_exp_f32_e32 v87, v87
	v_exp_f32_e32 v82, v82
	v_exp_f32_e32 v83, v83
	v_and_b32_e32 v89, 0xffff0000, v137
	v_add_f32_e32 v85, 1.0, v85
	v_add_f32_e32 v94, 1.0, v86
	v_rcp_f32_e32 v86, v85
	v_add_f32_e32 v85, 1.0, v88
	v_mul_f32_e32 v88, 0xbfb8aa3b, v89
	v_exp_f32_e32 v89, v88
	v_rcp_f32_e32 v88, v85
	v_add_f32_e32 v85, 1.0, v87
	v_add_f32_e32 v82, 1.0, v82
	v_add_f32_e32 v83, 1.0, v83
	v_rcp_f32_e32 v87, v85
	v_rcp_f32_e32 v82, v82
	v_rcp_f32_e32 v83, v83
	v_add_f32_e32 v85, 1.0, v89
	v_pk_mul_f32 v[80:81], v[80:81], v[86:87]
	v_lshl_add_u64 v[86:87], v[170:171], 0, s[18:19]
	v_pk_mul_f32 v[78:79], v[78:79], v[82:83]
	v_lshl_add_u64 v[82:83], v[168:169], 0, v[86:87]
	global_load_dwordx4 v[110:113], v[82:83], off offset:256
	global_load_dwordx4 v[126:129], v[82:83], off
	v_rcp_f32_e32 v89, v85
	v_lshlrev_b32_e32 v84, 16, v136
	v_mul_f32_e32 v84, 0xbfb8aa3b, v84
	v_exp_f32_e32 v84, v84
	v_pk_mul_f32 v[76:77], v[76:77], v[88:89]
	v_cvt_pk_bf16_f32 v118, v78, v79
	v_cvt_pk_bf16_f32 v121, v76, v77
	v_lshlrev_b32_e32 v77, 16, v131
	v_cvt_pk_bf16_f32 v119, v80, v81
	v_and_b32_e32 v78, 0xffff0000, v132
	v_lshlrev_b32_e32 v80, 16, v133
	v_mul_f32_e32 v77, 0xbfb8aa3b, v77
	v_add_f32_e32 v84, 1.0, v84
	v_mul_f32_e32 v78, 0xbfb8aa3b, v78
	v_exp_f32_e32 v77, v77
	v_mul_f32_e32 v80, 0xbfb8aa3b, v80
	v_rcp_f32_e32 v84, v84
	v_rcp_f32_e32 v85, v94
	v_exp_f32_e32 v78, v78
	v_exp_f32_e32 v80, v80
	v_and_b32_e32 v79, 0xffff0000, v131
	v_lshlrev_b32_e32 v76, 16, v132
	v_and_b32_e32 v81, 0xffff0000, v133
	v_add_f32_e32 v77, 1.0, v77
	v_mul_f32_e32 v79, 0xbfb8aa3b, v79
	v_pk_mul_f32 v[74:75], v[74:75], v[84:85]
	v_mul_f32_e32 v76, 0xbfb8aa3b, v76
	v_add_f32_e32 v84, 1.0, v78
	v_rcp_f32_e32 v78, v77
	v_add_f32_e32 v77, 1.0, v80
	v_exp_f32_e32 v79, v79
	v_mul_f32_e32 v80, 0xbfb8aa3b, v81
	v_exp_f32_e32 v76, v76
	v_exp_f32_e32 v81, v80
	v_rcp_f32_e32 v80, v77
	v_add_f32_e32 v77, 1.0, v79
	v_add_f32_e32 v76, 1.0, v76
	v_rcp_f32_e32 v79, v77
	v_add_f32_e32 v77, 1.0, v81
	v_rcp_f32_e32 v76, v76
	v_rcp_f32_e32 v81, v77
	v_rcp_f32_e32 v77, v84
	v_lshl_add_u64 v[88:89], v[170:171], 0, s[20:21]
	v_cvt_pk_bf16_f32 v120, v74, v75
	v_lshlrev_b32_e32 v74, 16, v130
	v_pk_mul_f32 v[66:67], v[66:67], v[76:77]
	v_and_b32_e32 v75, 0xffff0000, v130
	v_cvt_pk_bf16_f32 v132, v66, v67
	v_lshl_add_u64 v[66:67], v[168:169], 0, v[88:89]
	global_load_dwordx4 v[134:137], v[66:67], off offset:256
	global_load_dwordx4 v[82:85], v[66:67], off
	v_mul_f32_e32 v74, 0xbfb8aa3b, v74
	v_mul_f32_e32 v75, 0xbfb8aa3b, v75
	v_exp_f32_e32 v74, v74
	v_exp_f32_e32 v75, v75
	v_lshl_add_u64 v[94:95], v[170:171], 0, s[22:23]
	v_lshl_add_u64 v[66:67], v[168:169], 0, v[94:95]
	v_add_f32_e32 v74, 1.0, v74
	v_add_f32_e32 v75, 1.0, v75
	v_rcp_f32_e32 v74, v74
	v_rcp_f32_e32 v75, v75
	v_lshl_add_u64 v[96:97], v[170:171], 0, s[8:9]
	v_lshl_add_u64 v[138:139], s[6:7], 0, v[170:171]
	v_pk_mul_f32 v[72:73], v[72:73], v[78:79]
	v_pk_mul_f32 v[70:71], v[70:71], v[74:75]
	v_pk_mul_f32 v[68:69], v[68:69], v[80:81]
	global_load_dwordx4 v[78:81], v[66:67], off offset:256
	global_load_dwordx4 v[74:77], v[66:67], off
	v_lshl_add_u64 v[66:67], v[168:169], 0, v[96:97]
	v_lshl_add_u64 v[138:139], v[138:139], 0, v[166:167]
	v_cvt_pk_bf16_f32 v130, v70, v71
	v_cvt_pk_bf16_f32 v131, v72, v73
	v_cvt_pk_bf16_f32 v133, v68, v69
	global_load_dwordx4 v[70:73], v[66:67], off offset:256
	s_nop 0
	global_load_dwordx4 v[66:69], v[66:67], off
	s_nop 0
	global_store_dwordx4 v[138:139], v[122:125], off
	global_store_dwordx4 v[138:139], v[114:117], off offset:256
	s_nop 1
	v_lshl_add_u64 v[114:115], s[6:7], 0, v[176:177]
	v_lshl_add_u64 v[114:115], v[114:115], 0, v[166:167]
	global_store_dwordx4 v[114:115], v[106:109], off
	global_store_dwordx4 v[114:115], v[98:101], off offset:256
	s_nop 1
	v_lshl_add_u64 v[98:99], s[6:7], 0, v[174:175]
	v_lshl_add_u64 v[98:99], v[98:99], 0, v[166:167]
	global_store_dwordx4 v[98:99], v[90:93], off
	global_store_dwordx4 v[98:99], v[102:105], off offset:256
	s_waitcnt vmcnt(13)
	v_lshlrev_b32_e32 v98, 16, v111
	v_lshlrev_b32_e32 v92, 16, v110
	v_and_b32_e32 v93, 0xffff0000, v110
	v_and_b32_e32 v99, 0xffff0000, v111
	v_mul_f32_e32 v92, 0xbfb8aa3b, v92
	v_mul_f32_e32 v93, 0xbfb8aa3b, v93
	v_mul_f32_e32 v98, 0xbfb8aa3b, v98
	v_mul_f32_e32 v99, 0xbfb8aa3b, v99
	v_exp_f32_e32 v92, v92
	v_exp_f32_e32 v93, v93
	v_exp_f32_e32 v98, v98
	v_exp_f32_e32 v99, v99
	v_lshl_add_u64 v[90:91], s[6:7], 0, v[172:173]
	v_lshl_add_u64 v[90:91], v[90:91], 0, v[166:167]
	global_store_dwordx4 v[90:91], v[118:121], off
	v_lshlrev_b32_e32 v100, 16, v112
	global_store_dwordx4 v[90:91], v[130:133], off offset:256
	v_and_b32_e32 v91, 0xffff0000, v112
	v_add_f32_e32 v92, 1.0, v92
	v_add_f32_e32 v93, 1.0, v93
	v_add_f32_e32 v98, 1.0, v98
	v_add_f32_e32 v99, 1.0, v99
	v_mul_f32_e32 v100, 0xbfb8aa3b, v100
	v_mul_f32_e32 v91, 0xbfb8aa3b, v91
	v_rcp_f32_e32 v92, v92
	v_rcp_f32_e32 v93, v93
	v_rcp_f32_e32 v98, v98
	v_rcp_f32_e32 v99, v99
	v_exp_f32_e32 v100, v100
	v_exp_f32_e32 v91, v91
	v_pk_mul_f32 v[62:63], v[62:63], v[92:93]
	v_pk_mul_f32 v[64:65], v[64:65], v[98:99]
	v_add_f32_e32 v90, 1.0, v100
	v_add_f32_e32 v91, 1.0, v91
	v_rcp_f32_e32 v90, v90
	v_rcp_f32_e32 v91, v91
	v_cvt_pk_bf16_f32 v62, v62, v63
	v_cvt_pk_bf16_f32 v63, v64, v65
	s_waitcnt vmcnt(14)
	v_lshlrev_b32_e32 v64, 16, v126
	v_mul_f32_e32 v64, 0xbfb8aa3b, v64
	v_exp_f32_e32 v65, v64
	v_and_b32_e32 v64, 0xffff0000, v126
	v_mul_f32_e32 v64, 0xbfb8aa3b, v64
	v_pk_mul_f32 v[58:59], v[58:59], v[90:91]
	v_exp_f32_e32 v90, v64
	v_lshlrev_b32_e32 v92, 16, v113
	v_and_b32_e32 v93, 0xffff0000, v113
	v_mul_f32_e32 v92, 0xbfb8aa3b, v92
	v_mul_f32_e32 v93, 0xbfb8aa3b, v93
	v_cvt_pk_bf16_f32 v64, v58, v59
	v_add_f32_e32 v58, 1.0, v65
	v_lshlrev_b32_e32 v65, 16, v127
	v_exp_f32_e32 v92, v92
	v_exp_f32_e32 v93, v93
	v_add_f32_e32 v59, 1.0, v90
	v_mul_f32_e32 v65, 0xbfb8aa3b, v65
	v_and_b32_e32 v90, 0xffff0000, v127
	v_exp_f32_e32 v65, v65
	v_mul_f32_e32 v90, 0xbfb8aa3b, v90
	v_exp_f32_e32 v91, v90
	v_rcp_f32_e32 v58, v58
	v_rcp_f32_e32 v59, v59
	v_add_f32_e32 v92, 1.0, v92
	v_add_f32_e32 v93, 1.0, v93
	v_rcp_f32_e32 v92, v92
	v_rcp_f32_e32 v93, v93
	v_add_f32_e32 v65, 1.0, v65
	v_rcp_f32_e32 v90, v65
	v_add_f32_e32 v65, 1.0, v91
	v_rcp_f32_e32 v91, v65
	v_lshlrev_b32_e32 v65, 16, v128
	v_pk_mul_f32 v[54:55], v[54:55], v[58:59]
	v_and_b32_e32 v59, 0xffff0000, v128
	v_mul_f32_e32 v65, 0xbfb8aa3b, v65
	v_mul_f32_e32 v59, 0xbfb8aa3b, v59
	v_pk_mul_f32 v[60:61], v[60:61], v[92:93]
	v_exp_f32_e32 v92, v65
	v_exp_f32_e32 v59, v59
	v_pk_mul_f32 v[56:57], v[56:57], v[90:91]
	v_cvt_pk_bf16_f32 v54, v54, v55
	v_add_f32_e32 v58, 1.0, v92
	v_add_f32_e32 v59, 1.0, v59
	v_rcp_f32_e32 v58, v58
	v_rcp_f32_e32 v59, v59
	v_cvt_pk_bf16_f32 v55, v56, v57
	s_waitcnt vmcnt(13)
	v_lshlrev_b32_e32 v56, 16, v134
	v_mul_f32_e32 v56, 0xbfb8aa3b, v56
	v_exp_f32_e32 v57, v56
	v_and_b32_e32 v56, 0xffff0000, v134
	v_mul_f32_e32 v56, 0xbfb8aa3b, v56
	v_pk_mul_f32 v[50:51], v[50:51], v[58:59]
	v_exp_f32_e32 v58, v56
	v_cvt_pk_bf16_f32 v65, v60, v61
	v_lshlrev_b32_e32 v60, 16, v129
	v_and_b32_e32 v61, 0xffff0000, v129
	v_mul_f32_e32 v60, 0xbfb8aa3b, v60
	v_mul_f32_e32 v61, 0xbfb8aa3b, v61
	v_cvt_pk_bf16_f32 v56, v50, v51
	v_add_f32_e32 v50, 1.0, v57
	v_lshlrev_b32_e32 v57, 16, v135
	v_exp_f32_e32 v60, v60
	v_exp_f32_e32 v61, v61
	v_add_f32_e32 v51, 1.0, v58
	v_mul_f32_e32 v57, 0xbfb8aa3b, v57
	v_and_b32_e32 v58, 0xffff0000, v135
	v_exp_f32_e32 v57, v57
	v_mul_f32_e32 v58, 0xbfb8aa3b, v58
	v_exp_f32_e32 v59, v58
	v_rcp_f32_e32 v50, v50
	v_rcp_f32_e32 v51, v51
	v_add_f32_e32 v60, 1.0, v60
	v_add_f32_e32 v61, 1.0, v61
	v_rcp_f32_e32 v60, v60
	v_rcp_f32_e32 v61, v61
	v_add_f32_e32 v57, 1.0, v57
	v_rcp_f32_e32 v58, v57
	v_add_f32_e32 v57, 1.0, v59
	v_rcp_f32_e32 v59, v57
	v_lshlrev_b32_e32 v57, 16, v136
	v_pk_mul_f32 v[46:47], v[46:47], v[50:51]
	v_and_b32_e32 v51, 0xffff0000, v136
	v_mul_f32_e32 v57, 0xbfb8aa3b, v57
	v_mul_f32_e32 v51, 0xbfb8aa3b, v51
	v_pk_mul_f32 v[52:53], v[52:53], v[60:61]
	v_exp_f32_e32 v60, v57
	v_exp_f32_e32 v51, v51
	v_pk_mul_f32 v[48:49], v[48:49], v[58:59]
	v_cvt_pk_bf16_f32 v46, v46, v47
	v_add_f32_e32 v50, 1.0, v60
	v_add_f32_e32 v51, 1.0, v51
	v_rcp_f32_e32 v50, v50
	v_rcp_f32_e32 v51, v51
	v_cvt_pk_bf16_f32 v47, v48, v49
	s_waitcnt vmcnt(12)
	v_lshlrev_b32_e32 v48, 16, v82
	v_mul_f32_e32 v48, 0xbfb8aa3b, v48
	v_exp_f32_e32 v49, v48
	v_and_b32_e32 v48, 0xffff0000, v82
	v_mul_f32_e32 v48, 0xbfb8aa3b, v48
	v_pk_mul_f32 v[42:43], v[42:43], v[50:51]
	v_exp_f32_e32 v50, v48
	v_cvt_pk_bf16_f32 v57, v52, v53
	v_lshlrev_b32_e32 v52, 16, v137
	v_and_b32_e32 v53, 0xffff0000, v137
	v_mul_f32_e32 v52, 0xbfb8aa3b, v52
	v_mul_f32_e32 v53, 0xbfb8aa3b, v53
	v_cvt_pk_bf16_f32 v48, v42, v43
	v_add_f32_e32 v42, 1.0, v49
	v_lshlrev_b32_e32 v49, 16, v83
	v_exp_f32_e32 v52, v52
	v_exp_f32_e32 v53, v53
	v_add_f32_e32 v43, 1.0, v50
	v_mul_f32_e32 v49, 0xbfb8aa3b, v49
	v_and_b32_e32 v50, 0xffff0000, v83
	v_exp_f32_e32 v49, v49
	v_mul_f32_e32 v50, 0xbfb8aa3b, v50
	v_exp_f32_e32 v51, v50
	v_rcp_f32_e32 v42, v42
	v_rcp_f32_e32 v43, v43
	v_add_f32_e32 v52, 1.0, v52
	v_add_f32_e32 v53, 1.0, v53
	v_rcp_f32_e32 v52, v52
	v_rcp_f32_e32 v53, v53
	v_add_f32_e32 v49, 1.0, v49
	v_rcp_f32_e32 v50, v49
	v_add_f32_e32 v49, 1.0, v51
	v_rcp_f32_e32 v51, v49
	v_lshlrev_b32_e32 v49, 16, v84
	v_pk_mul_f32 v[38:39], v[38:39], v[42:43]
	v_and_b32_e32 v43, 0xffff0000, v84
	v_mul_f32_e32 v49, 0xbfb8aa3b, v49
	v_mul_f32_e32 v43, 0xbfb8aa3b, v43
	v_pk_mul_f32 v[44:45], v[44:45], v[52:53]
	v_exp_f32_e32 v52, v49
	v_exp_f32_e32 v43, v43
	v_pk_mul_f32 v[40:41], v[40:41], v[50:51]
	v_cvt_pk_bf16_f32 v38, v38, v39
	v_add_f32_e32 v42, 1.0, v52
	v_add_f32_e32 v43, 1.0, v43
	v_rcp_f32_e32 v42, v42
	v_rcp_f32_e32 v43, v43
	v_cvt_pk_bf16_f32 v39, v40, v41
	s_waitcnt vmcnt(11)
	v_lshlrev_b32_e32 v40, 16, v78
	v_mul_f32_e32 v40, 0xbfb8aa3b, v40
	v_exp_f32_e32 v41, v40
	v_and_b32_e32 v40, 0xffff0000, v78
	v_mul_f32_e32 v40, 0xbfb8aa3b, v40
	v_pk_mul_f32 v[34:35], v[34:35], v[42:43]
	v_exp_f32_e32 v42, v40
	v_cvt_pk_bf16_f32 v49, v44, v45
	v_lshlrev_b32_e32 v44, 16, v85
	v_and_b32_e32 v45, 0xffff0000, v85
	v_mul_f32_e32 v44, 0xbfb8aa3b, v44
	v_mul_f32_e32 v45, 0xbfb8aa3b, v45
	v_cvt_pk_bf16_f32 v40, v34, v35
	v_add_f32_e32 v34, 1.0, v41
	v_lshlrev_b32_e32 v41, 16, v79
	v_exp_f32_e32 v44, v44
	v_exp_f32_e32 v45, v45
	v_add_f32_e32 v35, 1.0, v42
	v_mul_f32_e32 v41, 0xbfb8aa3b, v41
	v_and_b32_e32 v42, 0xffff0000, v79
	v_exp_f32_e32 v41, v41
	v_mul_f32_e32 v42, 0xbfb8aa3b, v42
	v_exp_f32_e32 v43, v42
	v_rcp_f32_e32 v34, v34
	v_rcp_f32_e32 v35, v35
	v_add_f32_e32 v44, 1.0, v44
	v_add_f32_e32 v45, 1.0, v45
	v_rcp_f32_e32 v44, v44
	v_rcp_f32_e32 v45, v45
	v_add_f32_e32 v41, 1.0, v41
	v_rcp_f32_e32 v42, v41
	v_add_f32_e32 v41, 1.0, v43
	v_rcp_f32_e32 v43, v41
	v_lshlrev_b32_e32 v41, 16, v80
	v_pk_mul_f32 v[30:31], v[30:31], v[34:35]
	v_and_b32_e32 v35, 0xffff0000, v80
	v_mul_f32_e32 v41, 0xbfb8aa3b, v41
	v_mul_f32_e32 v35, 0xbfb8aa3b, v35
	v_pk_mul_f32 v[36:37], v[36:37], v[44:45]
	v_exp_f32_e32 v44, v41
	v_exp_f32_e32 v35, v35
	v_pk_mul_f32 v[32:33], v[32:33], v[42:43]
	v_cvt_pk_bf16_f32 v30, v30, v31
	v_add_f32_e32 v34, 1.0, v44
	v_add_f32_e32 v35, 1.0, v35
	v_rcp_f32_e32 v34, v34
	v_rcp_f32_e32 v35, v35
	v_cvt_pk_bf16_f32 v31, v32, v33
	s_waitcnt vmcnt(10)
	v_lshlrev_b32_e32 v32, 16, v74
	v_mul_f32_e32 v32, 0xbfb8aa3b, v32
	v_exp_f32_e32 v33, v32
	v_and_b32_e32 v32, 0xffff0000, v74
	v_mul_f32_e32 v32, 0xbfb8aa3b, v32
	v_pk_mul_f32 v[26:27], v[26:27], v[34:35]
	v_exp_f32_e32 v34, v32
	v_cvt_pk_bf16_f32 v41, v36, v37
	v_lshlrev_b32_e32 v36, 16, v81
	v_and_b32_e32 v37, 0xffff0000, v81
	v_mul_f32_e32 v36, 0xbfb8aa3b, v36
	v_mul_f32_e32 v37, 0xbfb8aa3b, v37
	v_cvt_pk_bf16_f32 v32, v26, v27
	v_add_f32_e32 v26, 1.0, v33
	v_lshlrev_b32_e32 v33, 16, v75
	v_exp_f32_e32 v36, v36
	v_exp_f32_e32 v37, v37
	v_add_f32_e32 v27, 1.0, v34
	v_mul_f32_e32 v33, 0xbfb8aa3b, v33
	v_and_b32_e32 v34, 0xffff0000, v75
	v_exp_f32_e32 v33, v33
	v_mul_f32_e32 v34, 0xbfb8aa3b, v34
	v_exp_f32_e32 v35, v34
	v_rcp_f32_e32 v26, v26
	v_rcp_f32_e32 v27, v27
	v_add_f32_e32 v36, 1.0, v36
	v_add_f32_e32 v37, 1.0, v37
	v_rcp_f32_e32 v36, v36
	v_rcp_f32_e32 v37, v37
	v_add_f32_e32 v33, 1.0, v33
	v_rcp_f32_e32 v34, v33
	v_add_f32_e32 v33, 1.0, v35
	v_rcp_f32_e32 v35, v33
	v_lshlrev_b32_e32 v33, 16, v76
	v_pk_mul_f32 v[22:23], v[22:23], v[26:27]
	v_and_b32_e32 v27, 0xffff0000, v76
	v_mul_f32_e32 v33, 0xbfb8aa3b, v33
	v_mul_f32_e32 v27, 0xbfb8aa3b, v27
	v_pk_mul_f32 v[28:29], v[28:29], v[36:37]
	v_exp_f32_e32 v36, v33
	v_exp_f32_e32 v27, v27
	v_pk_mul_f32 v[24:25], v[24:25], v[34:35]
	v_cvt_pk_bf16_f32 v22, v22, v23
	v_add_f32_e32 v26, 1.0, v36
	v_add_f32_e32 v27, 1.0, v27
	v_rcp_f32_e32 v26, v26
	v_rcp_f32_e32 v27, v27
	v_cvt_pk_bf16_f32 v23, v24, v25
	s_waitcnt vmcnt(9)
	v_lshlrev_b32_e32 v24, 16, v70
	v_mul_f32_e32 v24, 0xbfb8aa3b, v24
	v_exp_f32_e32 v25, v24
	v_and_b32_e32 v24, 0xffff0000, v70
	v_mul_f32_e32 v24, 0xbfb8aa3b, v24
	v_pk_mul_f32 v[18:19], v[18:19], v[26:27]
	v_exp_f32_e32 v26, v24
	v_cvt_pk_bf16_f32 v33, v28, v29
	v_lshlrev_b32_e32 v28, 16, v77
	v_and_b32_e32 v29, 0xffff0000, v77
	v_mul_f32_e32 v28, 0xbfb8aa3b, v28
	v_mul_f32_e32 v29, 0xbfb8aa3b, v29
	v_cvt_pk_bf16_f32 v24, v18, v19
	v_add_f32_e32 v18, 1.0, v25
	v_lshlrev_b32_e32 v25, 16, v71
	v_exp_f32_e32 v28, v28
	v_exp_f32_e32 v29, v29
	v_add_f32_e32 v19, 1.0, v26
	v_mul_f32_e32 v25, 0xbfb8aa3b, v25
	v_and_b32_e32 v26, 0xffff0000, v71
	v_exp_f32_e32 v25, v25
	v_mul_f32_e32 v26, 0xbfb8aa3b, v26
	v_exp_f32_e32 v27, v26
	v_rcp_f32_e32 v18, v18
	v_rcp_f32_e32 v19, v19
	v_add_f32_e32 v28, 1.0, v28
	v_add_f32_e32 v29, 1.0, v29
	v_rcp_f32_e32 v28, v28
	v_rcp_f32_e32 v29, v29
	v_add_f32_e32 v25, 1.0, v25
	v_rcp_f32_e32 v26, v25
	v_add_f32_e32 v25, 1.0, v27
	v_rcp_f32_e32 v27, v25
	v_lshlrev_b32_e32 v25, 16, v72
	v_pk_mul_f32 v[14:15], v[14:15], v[18:19]
	v_and_b32_e32 v19, 0xffff0000, v72
	v_mul_f32_e32 v25, 0xbfb8aa3b, v25
	v_mul_f32_e32 v19, 0xbfb8aa3b, v19
	v_pk_mul_f32 v[20:21], v[20:21], v[28:29]
	v_exp_f32_e32 v28, v25
	v_exp_f32_e32 v19, v19
	v_pk_mul_f32 v[16:17], v[16:17], v[26:27]
	v_cvt_pk_bf16_f32 v14, v14, v15
	v_add_f32_e32 v18, 1.0, v28
	v_add_f32_e32 v19, 1.0, v19
	v_rcp_f32_e32 v18, v18
	v_rcp_f32_e32 v19, v19
	v_cvt_pk_bf16_f32 v15, v16, v17
	s_waitcnt vmcnt(8)
	v_lshlrev_b32_e32 v16, 16, v66
	v_mul_f32_e32 v16, 0xbfb8aa3b, v16
	v_exp_f32_e32 v17, v16
	v_and_b32_e32 v16, 0xffff0000, v66
	v_mul_f32_e32 v16, 0xbfb8aa3b, v16
	v_pk_mul_f32 v[10:11], v[10:11], v[18:19]
	v_exp_f32_e32 v18, v16
	v_cvt_pk_bf16_f32 v25, v20, v21
	v_lshlrev_b32_e32 v20, 16, v73
	v_and_b32_e32 v21, 0xffff0000, v73
	v_mul_f32_e32 v20, 0xbfb8aa3b, v20
	v_mul_f32_e32 v21, 0xbfb8aa3b, v21
	v_exp_f32_e32 v20, v20
	v_exp_f32_e32 v21, v21
	v_cvt_pk_bf16_f32 v16, v10, v11
	v_add_f32_e32 v10, 1.0, v17
	v_lshlrev_b32_e32 v17, 16, v67
	v_add_f32_e32 v11, 1.0, v18
	v_mul_f32_e32 v17, 0xbfb8aa3b, v17
	v_and_b32_e32 v18, 0xffff0000, v67
	v_exp_f32_e32 v17, v17
	v_mul_f32_e32 v18, 0xbfb8aa3b, v18
	v_exp_f32_e32 v19, v18
	v_add_f32_e32 v20, 1.0, v20
	v_add_f32_e32 v21, 1.0, v21
	v_rcp_f32_e32 v20, v20
	v_rcp_f32_e32 v21, v21
	v_rcp_f32_e32 v10, v10
	v_rcp_f32_e32 v11, v11
	v_add_f32_e32 v17, 1.0, v17
	v_rcp_f32_e32 v18, v17
	v_add_f32_e32 v17, 1.0, v19
	v_rcp_f32_e32 v19, v17
	v_lshlrev_b32_e32 v17, 16, v68
	v_pk_mul_f32 v[12:13], v[12:13], v[20:21]
	v_mul_f32_e32 v17, 0xbfb8aa3b, v17
	v_pk_mul_f32 v[6:7], v[6:7], v[10:11]
	v_and_b32_e32 v11, 0xffff0000, v68
	v_exp_f32_e32 v20, v17
	v_cvt_pk_bf16_f32 v17, v12, v13
	v_mul_f32_e32 v11, 0xbfb8aa3b, v11
	v_lshlrev_b32_e32 v12, 16, v69
	v_and_b32_e32 v13, 0xffff0000, v69
	v_exp_f32_e32 v11, v11
	v_mul_f32_e32 v12, 0xbfb8aa3b, v12
	v_mul_f32_e32 v13, 0xbfb8aa3b, v13
	v_exp_f32_e32 v12, v12
	v_exp_f32_e32 v13, v13
	v_add_f32_e32 v10, 1.0, v20
	v_add_f32_e32 v11, 1.0, v11
	v_rcp_f32_e32 v10, v10
	v_add_f32_e32 v12, 1.0, v12
	v_add_f32_e32 v13, 1.0, v13
	v_rcp_f32_e32 v11, v11
	v_rcp_f32_e32 v12, v12
	v_rcp_f32_e32 v13, v13
	v_pk_mul_f32 v[8:9], v[8:9], v[18:19]
	v_pk_mul_f32 v[2:3], v[2:3], v[10:11]
	v_cvt_pk_bf16_f32 v6, v6, v7
	v_cvt_pk_bf16_f32 v7, v8, v9
	v_pk_mul_f32 v[4:5], v[4:5], v[12:13]
	v_cvt_pk_bf16_f32 v8, v2, v3
	v_lshl_add_u64 v[2:3], s[6:7], 0, v[96:97]
	v_cvt_pk_bf16_f32 v9, v4, v5
	v_lshl_add_u64 v[2:3], v[2:3], 0, v[166:167]
	global_store_dwordx4 v[2:3], v[6:9], off
	global_store_dwordx4 v[2:3], v[14:17], off offset:256
	v_lshl_add_u64 v[2:3], s[6:7], 0, v[94:95]
	v_lshl_add_u64 v[2:3], v[2:3], 0, v[166:167]
	global_store_dwordx4 v[2:3], v[22:25], off
	global_store_dwordx4 v[2:3], v[30:33], off offset:256
	v_lshl_add_u64 v[2:3], s[6:7], 0, v[88:89]
	v_lshl_add_u64 v[2:3], v[2:3], 0, v[166:167]
	global_store_dwordx4 v[2:3], v[38:41], off
	global_store_dwordx4 v[2:3], v[46:49], off offset:256
	v_lshl_add_u64 v[2:3], s[6:7], 0, v[86:87]
	v_lshl_add_u64 v[2:3], v[2:3], 0, v[166:167]
	global_store_dwordx4 v[2:3], v[54:57], off
	global_store_dwordx4 v[2:3], v[62:65], off offset:256
	s_cbranch_vccnz .LBB0_763
	s_andn2_b64 vcc, exec, s[10:11]
	s_cbranch_vccnz .LBB0_762
	s_barrier
	s_branch .LBB0_762

.LBB0_796:
	ds_read_b128 v[130:133], v162
	ds_read_b128 v[134:137], v162 offset:1024
	ds_read_b128 v[154:157], v162 offset:2048
	ds_read_b128 v[166:169], v162 offset:3072
	ds_read_b128 v[170:173], v163
	ds_read_b128 v[174:177], v163 offset:1024
	ds_read_b128 v[178:181], v163 offset:2048
	ds_read_b128 v[182:185], v163 offset:3072
	s_add_u32 s28, s0, 0xfff80080
	s_addc_u32 s29, s1, -1
	s_cmp_eq_u32 s54, 28
	s_cselect_b32 s31, s21, s29
	s_cselect_b32 s30, s50, s28
	s_cselect_b32 s29, s19, s53
	s_cselect_b32 s28, s51, s52
	v_lshl_add_u64 v[158:159], s[0:1], 0, v[146:147]
	s_add_i32 m0, s27, 0xc000
	ds_read_b128 v[186:189], v164
	ds_read_b128 v[190:193], v164 offset:1024
	ds_read_b128 v[194:197], v164 offset:2048
	ds_read_b128 v[198:201], v164 offset:3072
	ds_read_b128 v[202:205], v164 offset:4096
	ds_read_b128 v[206:209], v164 offset:5120
	ds_read_b128 v[210:213], v164 offset:6144
	ds_read_b128 v[214:217], v164 offset:7168
	global_load_lds_dwordx4 v[158:159], off
	v_lshl_add_u64 v[158:159], s[0:1], 0, v[148:149]
	s_add_i32 m0, s27, 0xe000
	s_nop 0
	global_load_lds_dwordx4 v[158:159], off
	s_waitcnt vmcnt(8)
	s_waitcnt lgkmcnt(0)
	s_barrier
	s_setprio 1
	s_waitcnt lgkmcnt(0)
	v_mfma_f32_16x16x32_bf16 v[126:129], v[130:133], v[186:189], v[126:129]
	v_mfma_f32_16x16x32_bf16 v[122:125], v[154:157], v[186:189], v[122:125]
	v_mfma_f32_16x16x32_bf16 v[110:113], v[130:133], v[194:197], v[110:113]
	v_mfma_f32_16x16x32_bf16 v[106:109], v[154:157], v[194:197], v[106:109]
	v_mfma_f32_16x16x32_bf16 v[94:97], v[130:133], v[202:205], v[94:97]
	v_mfma_f32_16x16x32_bf16 v[90:93], v[154:157], v[202:205], v[90:93]
	v_mfma_f32_16x16x32_bf16 v[78:81], v[130:133], v[210:213], v[78:81]
	v_mfma_f32_16x16x32_bf16 v[74:77], v[154:157], v[210:213], v[74:77]
	v_mfma_f32_16x16x32_bf16 v[126:129], v[134:137], v[190:193], v[126:129]
	v_mfma_f32_16x16x32_bf16 v[122:125], v[166:169], v[190:193], v[122:125]
	v_mfma_f32_16x16x32_bf16 v[110:113], v[134:137], v[198:201], v[110:113]
	v_mfma_f32_16x16x32_bf16 v[106:109], v[166:169], v[198:201], v[106:109]
	v_mfma_f32_16x16x32_bf16 v[94:97], v[134:137], v[206:209], v[94:97]
	v_mfma_f32_16x16x32_bf16 v[90:93], v[166:169], v[206:209], v[90:93]
	v_mfma_f32_16x16x32_bf16 v[78:81], v[134:137], v[214:217], v[78:81]
	v_mfma_f32_16x16x32_bf16 v[74:77], v[166:169], v[214:217], v[74:77]
	s_setprio 0
	s_setprio 1
	v_mfma_f32_16x16x32_bf16 v[118:121], v[170:173], v[186:189], v[118:121]
	v_mfma_f32_16x16x32_bf16 v[114:117], v[178:181], v[186:189], v[114:117]
	v_mfma_f32_16x16x32_bf16 v[102:105], v[170:173], v[194:197], v[102:105]
	v_mfma_f32_16x16x32_bf16 v[98:101], v[178:181], v[194:197], v[98:101]
	v_mfma_f32_16x16x32_bf16 v[86:89], v[170:173], v[202:205], v[86:89]
	v_mfma_f32_16x16x32_bf16 v[82:85], v[178:181], v[202:205], v[82:85]
	v_mfma_f32_16x16x32_bf16 v[70:73], v[170:173], v[210:213], v[70:73]
	v_mfma_f32_16x16x32_bf16 v[66:69], v[178:181], v[210:213], v[66:69]
	v_mfma_f32_16x16x32_bf16 v[118:121], v[174:177], v[190:193], v[118:121]
	v_mfma_f32_16x16x32_bf16 v[114:117], v[182:185], v[190:193], v[114:117]
	v_mfma_f32_16x16x32_bf16 v[102:105], v[174:177], v[198:201], v[102:105]
	v_mfma_f32_16x16x32_bf16 v[98:101], v[182:185], v[198:201], v[98:101]
	v_mfma_f32_16x16x32_bf16 v[86:89], v[174:177], v[206:209], v[86:89]
	v_mfma_f32_16x16x32_bf16 v[82:85], v[182:185], v[206:209], v[82:85]
	v_mfma_f32_16x16x32_bf16 v[70:73], v[174:177], v[214:217], v[70:73]
	v_mfma_f32_16x16x32_bf16 v[66:69], v[182:185], v[214:217], v[66:69]
	s_setprio 0
	s_barrier
	s_add_i32 s55, s47, s39
	v_lshl_add_u64 v[158:159], s[28:29], 0, v[140:141]
	s_mov_b32 m0, s55
	ds_read_b128 v[186:189], v164 offset:16384
	ds_read_b128 v[190:193], v164 offset:17408
	ds_read_b128 v[194:197], v164 offset:18432
	ds_read_b128 v[198:201], v164 offset:19456
	ds_read_b128 v[202:205], v164 offset:20480
	ds_read_b128 v[206:209], v164 offset:21504
	ds_read_b128 v[210:213], v164 offset:22528
	ds_read_b128 v[214:217], v164 offset:23552
	global_load_lds_dwordx4 v[158:159], off
	s_add_i32 m0, s55, 0x2000
	s_add_u32 s56, s28, 0x80000
	v_lshl_add_u64 v[218:219], s[28:29], 0, v[144:145]
	s_addc_u32 s57, s29, 0
	s_add_i32 s55, s48, s39
	global_load_lds_dwordx4 v[218:219], off
	v_lshl_add_u64 v[220:221], s[56:57], 0, v[140:141]
	s_mov_b32 m0, s55
	v_lshl_add_u64 v[222:223], s[30:31], 0, v[142:143]
	global_load_lds_dwordx4 v[220:221], off
	v_lshl_add_u64 v[220:221], s[56:57], 0, v[144:145]
	s_add_i32 m0, s55, 0x2000
	s_nop 0
	global_load_lds_dwordx4 v[220:221], off
	v_lshl_add_u64 v[220:221], s[30:31], 0, v[138:139]
	s_mov_b32 m0, s27
	s_nop 0
	global_load_lds_dwordx4 v[220:221], off
	s_mov_b32 m0, s40
	s_nop 0
	global_load_lds_dwordx4 v[222:223], off
	s_waitcnt vmcnt(8)
	s_waitcnt lgkmcnt(0)
	s_barrier
	s_setprio 1
	s_waitcnt lgkmcnt(0)
	v_mfma_f32_16x16x32_bf16 v[62:65], v[130:133], v[186:189], v[62:65]
	v_mfma_f32_16x16x32_bf16 v[58:61], v[154:157], v[186:189], v[58:61]
	v_mfma_f32_16x16x32_bf16 v[46:49], v[130:133], v[194:197], v[46:49]
	v_mfma_f32_16x16x32_bf16 v[42:45], v[154:157], v[194:197], v[42:45]
	v_mfma_f32_16x16x32_bf16 v[6:9], v[130:133], v[202:205], v[6:9]
	v_mfma_f32_16x16x32_bf16 v[2:5], v[154:157], v[202:205], v[2:5]
	v_mfma_f32_16x16x32_bf16 v[22:25], v[130:133], v[210:213], v[22:25]
	v_mfma_f32_16x16x32_bf16 v[18:21], v[154:157], v[210:213], v[18:21]
	v_mfma_f32_16x16x32_bf16 v[62:65], v[134:137], v[190:193], v[62:65]
	v_mfma_f32_16x16x32_bf16 v[58:61], v[166:169], v[190:193], v[58:61]
	v_mfma_f32_16x16x32_bf16 v[46:49], v[134:137], v[198:201], v[46:49]
	v_mfma_f32_16x16x32_bf16 v[42:45], v[166:169], v[198:201], v[42:45]
	v_mfma_f32_16x16x32_bf16 v[6:9], v[134:137], v[206:209], v[6:9]
	v_mfma_f32_16x16x32_bf16 v[2:5], v[166:169], v[206:209], v[2:5]
	v_mfma_f32_16x16x32_bf16 v[22:25], v[134:137], v[214:217], v[22:25]
	v_mfma_f32_16x16x32_bf16 v[18:21], v[166:169], v[214:217], v[18:21]
	s_setprio 0
	s_setprio 1
	v_mfma_f32_16x16x32_bf16 v[54:57], v[170:173], v[186:189], v[54:57]
	v_mfma_f32_16x16x32_bf16 v[50:53], v[178:181], v[186:189], v[50:53]
	v_mfma_f32_16x16x32_bf16 v[38:41], v[170:173], v[194:197], v[38:41]
	v_mfma_f32_16x16x32_bf16 v[34:37], v[178:181], v[194:197], v[34:37]
	v_mfma_f32_16x16x32_bf16 v[14:17], v[170:173], v[202:205], v[14:17]
	v_mfma_f32_16x16x32_bf16 v[10:13], v[178:181], v[202:205], v[10:13]
	v_mfma_f32_16x16x32_bf16 v[30:33], v[170:173], v[210:213], v[30:33]
	v_mfma_f32_16x16x32_bf16 v[26:29], v[178:181], v[210:213], v[26:29]
	v_mfma_f32_16x16x32_bf16 v[54:57], v[174:177], v[190:193], v[54:57]
	v_mfma_f32_16x16x32_bf16 v[50:53], v[182:185], v[190:193], v[50:53]
	v_mfma_f32_16x16x32_bf16 v[38:41], v[174:177], v[198:201], v[38:41]
	v_mfma_f32_16x16x32_bf16 v[34:37], v[182:185], v[198:201], v[34:37]
	v_mfma_f32_16x16x32_bf16 v[14:17], v[174:177], v[206:209], v[14:17]
	v_mfma_f32_16x16x32_bf16 v[10:13], v[182:185], v[206:209], v[10:13]
	v_mfma_f32_16x16x32_bf16 v[30:33], v[174:177], v[214:217], v[30:33]
	v_mfma_f32_16x16x32_bf16 v[26:29], v[182:185], v[214:217], v[26:29]
	s_setprio 0
	s_barrier
	s_cmp_lg_u32 s54, 28
	s_cbranch_scc1 .Lmy_p6_nox
	v_lshl_add_u32 v152, s26, 8, v1
	v_lshl_or_b32 v153, s49, 8, v161
	v_lshl_add_u32 v152, v152, 10, v153
	v_lshlrev_b32_e32 v150, 1, v152
	v_add_u32_e32 v151, 0x8000, v150
	global_load_dwordx4 v[226:229], v150, s[8:9]
	global_load_dwordx4 v[230:233], v150, s[10:11]
	global_load_dwordx4 v[234:237], v150, s[8:9] offset:256
	global_load_dwordx4 v[238:241], v150, s[10:11] offset:256
	global_load_dwordx4 v[242:245], v151, s[8:9]
	global_load_dwordx4 v[246:249], v151, s[10:11]
	global_load_dwordx4 v[250:253], v151, s[8:9] offset:256
	global_load_dwordx4 v[150:153], v151, s[10:11] offset:256
.Lmy_p6_nox:
	s_add_i32 s55, 0, 0x18000
	v_add_u32_e32 v165, s55, v160
	s_add_i32 s56, 0, 0x1c000
	ds_read_b128 v[130:133], v165
	ds_read_b128 v[134:137], v165 offset:1024
	ds_read_b128 v[154:157], v165 offset:2048
	ds_read_b128 v[166:169], v165 offset:3072
	v_add_u32_e32 v165, s56, v160
	ds_read_b128 v[170:173], v165
	ds_read_b128 v[174:177], v165 offset:1024
	ds_read_b128 v[178:181], v165 offset:2048
	ds_read_b128 v[182:185], v165 offset:3072
	s_add_u32 s30, s30, 0x80000
	s_addc_u32 s31, s31, 0
	s_mov_b32 m0, s41
	v_lshl_add_u64 v[224:225], s[30:31], 0, v[138:139]
	ds_read_b128 v[186:189], v164 offset:32768
	ds_read_b128 v[190:193], v164 offset:33792
	ds_read_b128 v[194:197], v164 offset:34816
	ds_read_b128 v[198:201], v164 offset:35840
	ds_read_b128 v[202:205], v164 offset:36864
	ds_read_b128 v[206:209], v164 offset:37888
	ds_read_b128 v[210:213], v164 offset:38912
	ds_read_b128 v[214:217], v164 offset:39936
	global_load_lds_dwordx4 v[224:225], off
	v_lshl_add_u64 v[224:225], s[30:31], 0, v[142:143]
	s_mov_b32 m0, s42
	s_nop 0
	global_load_lds_dwordx4 v[224:225], off
	s_cmp_eq_u32 s54, 28
	s_cbranch_scc1 .Lmy_p6_wc_last
	s_waitcnt vmcnt(8)
	s_branch .Lmy_p6_wc_done

.Lmy_p6_wc_done:
	s_waitcnt lgkmcnt(0)
	s_barrier
	s_setprio 1
	s_waitcnt lgkmcnt(0)
	v_mfma_f32_16x16x32_bf16 v[126:129], v[130:133], v[186:189], v[126:129]
	v_mfma_f32_16x16x32_bf16 v[122:125], v[154:157], v[186:189], v[122:125]
	v_mfma_f32_16x16x32_bf16 v[110:113], v[130:133], v[194:197], v[110:113]
	v_mfma_f32_16x16x32_bf16 v[106:109], v[154:157], v[194:197], v[106:109]
	v_mfma_f32_16x16x32_bf16 v[94:97], v[130:133], v[202:205], v[94:97]
	v_mfma_f32_16x16x32_bf16 v[90:93], v[154:157], v[202:205], v[90:93]
	v_mfma_f32_16x16x32_bf16 v[78:81], v[130:133], v[210:213], v[78:81]
	v_mfma_f32_16x16x32_bf16 v[74:77], v[154:157], v[210:213], v[74:77]
	v_mfma_f32_16x16x32_bf16 v[126:129], v[134:137], v[190:193], v[126:129]
	v_mfma_f32_16x16x32_bf16 v[122:125], v[166:169], v[190:193], v[122:125]
	v_mfma_f32_16x16x32_bf16 v[110:113], v[134:137], v[198:201], v[110:113]
	v_mfma_f32_16x16x32_bf16 v[106:109], v[166:169], v[198:201], v[106:109]
	v_mfma_f32_16x16x32_bf16 v[94:97], v[134:137], v[206:209], v[94:97]
	v_mfma_f32_16x16x32_bf16 v[90:93], v[166:169], v[206:209], v[90:93]
	v_mfma_f32_16x16x32_bf16 v[78:81], v[134:137], v[214:217], v[78:81]
	v_mfma_f32_16x16x32_bf16 v[74:77], v[166:169], v[214:217], v[74:77]
	s_setprio 0
	s_setprio 1
	v_mfma_f32_16x16x32_bf16 v[118:121], v[170:173], v[186:189], v[118:121]
	v_mfma_f32_16x16x32_bf16 v[114:117], v[178:181], v[186:189], v[114:117]
	v_mfma_f32_16x16x32_bf16 v[102:105], v[170:173], v[194:197], v[102:105]
	v_mfma_f32_16x16x32_bf16 v[98:101], v[178:181], v[194:197], v[98:101]
	v_mfma_f32_16x16x32_bf16 v[86:89], v[170:173], v[202:205], v[86:89]
	v_mfma_f32_16x16x32_bf16 v[82:85], v[178:181], v[202:205], v[82:85]
	v_mfma_f32_16x16x32_bf16 v[70:73], v[170:173], v[210:213], v[70:73]
	v_mfma_f32_16x16x32_bf16 v[66:69], v[178:181], v[210:213], v[66:69]
	v_mfma_f32_16x16x32_bf16 v[118:121], v[174:177], v[190:193], v[118:121]
	v_mfma_f32_16x16x32_bf16 v[114:117], v[182:185], v[190:193], v[114:117]
	v_mfma_f32_16x16x32_bf16 v[102:105], v[174:177], v[198:201], v[102:105]
	v_mfma_f32_16x16x32_bf16 v[98:101], v[182:185], v[198:201], v[98:101]
	v_mfma_f32_16x16x32_bf16 v[86:89], v[174:177], v[206:209], v[86:89]
	v_mfma_f32_16x16x32_bf16 v[82:85], v[182:185], v[206:209], v[82:85]
	v_mfma_f32_16x16x32_bf16 v[70:73], v[174:177], v[214:217], v[70:73]
	v_mfma_f32_16x16x32_bf16 v[66:69], v[182:185], v[214:217], v[66:69]
	s_setprio 0
	s_barrier
	s_add_i32 s30, s55, s39
	v_lshl_add_u64 v[158:159], v[158:159], 0, s[14:15]
	s_mov_b32 m0, s30
	ds_read_b128 v[186:189], v164 offset:49152
	ds_read_b128 v[190:193], v164 offset:50176
	ds_read_b128 v[194:197], v164 offset:51200
	ds_read_b128 v[198:201], v164 offset:52224
	ds_read_b128 v[202:205], v164 offset:53248
	ds_read_b128 v[206:209], v164 offset:54272
	ds_read_b128 v[210:213], v164 offset:55296
	ds_read_b128 v[214:217], v164 offset:56320
	global_load_lds_dwordx4 v[158:159], off
	s_add_i32 m0, s30, 0x2000
	s_add_u32 s28, s28, 0x80080
	v_lshl_add_u64 v[158:159], v[218:219], 0, s[14:15]
	s_addc_u32 s29, s29, 0
	s_add_i32 s30, s56, s39
	global_load_lds_dwordx4 v[158:159], off
	v_lshl_add_u64 v[158:159], s[28:29], 0, v[140:141]
	s_mov_b32 m0, s30
	s_nop 0
	global_load_lds_dwordx4 v[158:159], off
	v_lshl_add_u64 v[158:159], s[28:29], 0, v[144:145]
	s_add_i32 m0, s30, 0x2000
	s_nop 0
	global_load_lds_dwordx4 v[158:159], off
	v_lshl_add_u64 v[158:159], v[220:221], 0, s[14:15]
	s_mov_b32 m0, s44
	s_nop 0
	global_load_lds_dwordx4 v[158:159], off
	v_lshl_add_u64 v[158:159], v[222:223], 0, s[14:15]
	s_mov_b32 m0, s45
	s_nop 0
	global_load_lds_dwordx4 v[158:159], off
	s_cmp_eq_u32 s54, 28
	s_cbranch_scc1 .Lmy_p6_wd_last
	s_waitcnt vmcnt(8)
	s_branch .Lmy_p6_wd_done

.Lmy_p6_wd_done:
	s_waitcnt lgkmcnt(0)
	s_barrier
	s_setprio 1
	s_waitcnt lgkmcnt(0)
	v_mfma_f32_16x16x32_bf16 v[62:65], v[130:133], v[186:189], v[62:65]
	v_mfma_f32_16x16x32_bf16 v[58:61], v[154:157], v[186:189], v[58:61]
	v_mfma_f32_16x16x32_bf16 v[46:49], v[130:133], v[194:197], v[46:49]
	v_mfma_f32_16x16x32_bf16 v[42:45], v[154:157], v[194:197], v[42:45]
	v_mfma_f32_16x16x32_bf16 v[6:9], v[130:133], v[202:205], v[6:9]
	v_mfma_f32_16x16x32_bf16 v[2:5], v[154:157], v[202:205], v[2:5]
	v_mfma_f32_16x16x32_bf16 v[22:25], v[130:133], v[210:213], v[22:25]
	v_mfma_f32_16x16x32_bf16 v[18:21], v[154:157], v[210:213], v[18:21]
	v_mfma_f32_16x16x32_bf16 v[62:65], v[134:137], v[190:193], v[62:65]
	v_mfma_f32_16x16x32_bf16 v[58:61], v[166:169], v[190:193], v[58:61]
	v_mfma_f32_16x16x32_bf16 v[46:49], v[134:137], v[198:201], v[46:49]
	v_mfma_f32_16x16x32_bf16 v[42:45], v[166:169], v[198:201], v[42:45]
	v_mfma_f32_16x16x32_bf16 v[6:9], v[134:137], v[206:209], v[6:9]
	v_mfma_f32_16x16x32_bf16 v[2:5], v[166:169], v[206:209], v[2:5]
	v_mfma_f32_16x16x32_bf16 v[22:25], v[134:137], v[214:217], v[22:25]
	v_mfma_f32_16x16x32_bf16 v[18:21], v[166:169], v[214:217], v[18:21]
	s_setprio 0
	s_setprio 1
	v_mfma_f32_16x16x32_bf16 v[54:57], v[170:173], v[186:189], v[54:57]
	v_mfma_f32_16x16x32_bf16 v[50:53], v[178:181], v[186:189], v[50:53]
	v_mfma_f32_16x16x32_bf16 v[38:41], v[170:173], v[194:197], v[38:41]
	v_mfma_f32_16x16x32_bf16 v[34:37], v[178:181], v[194:197], v[34:37]
	v_mfma_f32_16x16x32_bf16 v[14:17], v[170:173], v[202:205], v[14:17]
	v_mfma_f32_16x16x32_bf16 v[10:13], v[178:181], v[202:205], v[10:13]
	v_mfma_f32_16x16x32_bf16 v[30:33], v[170:173], v[210:213], v[30:33]
	v_mfma_f32_16x16x32_bf16 v[26:29], v[178:181], v[210:213], v[26:29]
	v_mfma_f32_16x16x32_bf16 v[54:57], v[174:177], v[190:193], v[54:57]
	v_mfma_f32_16x16x32_bf16 v[50:53], v[182:185], v[190:193], v[50:53]
	v_mfma_f32_16x16x32_bf16 v[38:41], v[174:177], v[198:201], v[38:41]
	v_mfma_f32_16x16x32_bf16 v[34:37], v[182:185], v[198:201], v[34:37]
	v_mfma_f32_16x16x32_bf16 v[14:17], v[174:177], v[206:209], v[14:17]
	v_mfma_f32_16x16x32_bf16 v[10:13], v[182:185], v[206:209], v[10:13]
	v_mfma_f32_16x16x32_bf16 v[30:33], v[174:177], v[214:217], v[30:33]
	v_mfma_f32_16x16x32_bf16 v[26:29], v[182:185], v[214:217], v[26:29]
	s_setprio 0
	s_barrier
	s_add_i32 s54, s54, 2
	s_add_u32 s0, s0, 0x100
	s_addc_u32 s1, s1, 0
	s_add_u32 s52, s52, 0x100
	s_addc_u32 s53, s53, 0
	s_cmp_gt_u32 s54, 29
	s_cbranch_scc0 .LBB0_796
	s_and_b64 vcc, exec, s[16:17]
	s_cbranch_vccz .LBB0_799
	s_barrier
.LBB0_799:
	v_lshl_add_u32 v156, s26, 8, v1
	v_lshl_or_b32 v154, s49, 8, v161
	v_ashrrev_i32_e32 v157, 31, v156
	v_ashrrev_i32_e32 v155, 31, v154
	v_lshlrev_b64 v[130:131], 10, v[156:157]
	v_lshl_add_u64 v[130:131], v[130:131], 0, v[154:155]
	v_lshlrev_b64 v[130:131], 1, v[130:131]
	v_lshl_add_u64 v[132:133], s[8:9], 0, v[130:131]
	s_waitcnt vmcnt(8)
	v_mov_b32_e32 v166, v226
	v_mov_b32_e32 v167, v227
	v_mov_b32_e32 v168, v228
	v_mov_b32_e32 v169, v229
	v_lshl_add_u64 v[132:133], s[10:11], 0, v[130:131]
	v_or_b32_e32 v130, 0x100, v130
	v_mov_b32_e32 v170, v230
	v_mov_b32_e32 v171, v231
	v_mov_b32_e32 v172, v232
	v_mov_b32_e32 v173, v233
	v_lshl_add_u64 v[132:133], s[8:9], 0, v[130:131]
	v_lshl_add_u64 v[130:131], s[10:11], 0, v[130:131]
	v_mov_b32_e32 v174, v234
	v_mov_b32_e32 v175, v235
	v_mov_b32_e32 v176, v236
	v_mov_b32_e32 v177, v237
	v_mov_b32_e32 v178, v238
	v_mov_b32_e32 v179, v239
	v_mov_b32_e32 v180, v240
	v_mov_b32_e32 v181, v241
	v_or_b32_e32 v158, 16, v156
	v_ashrrev_i32_e32 v159, 31, v158
	v_lshlrev_b64 v[130:131], 10, v[158:159]
	v_lshl_add_u64 v[130:131], v[130:131], 0, v[154:155]
	v_lshlrev_b64 v[130:131], 1, v[130:131]
	v_lshl_add_u64 v[132:133], s[8:9], 0, v[130:131]
	v_lshl_add_u64 v[134:135], s[10:11], 0, v[130:131]
	v_mov_b32_e32 v182, v242
	v_mov_b32_e32 v183, v243
	v_mov_b32_e32 v184, v244
	v_mov_b32_e32 v185, v245
	v_mov_b32_e32 v186, v246
	v_mov_b32_e32 v187, v247
	v_mov_b32_e32 v188, v248
	v_mov_b32_e32 v189, v249
	v_or_b32_e32 v130, 0x100, v130
	v_lshl_add_u64 v[132:133], s[8:9], 0, v[130:131]
	v_lshl_add_u64 v[130:131], s[10:11], 0, v[130:131]
	v_mov_b32_e32 v134, v250
	v_mov_b32_e32 v135, v251
	v_mov_b32_e32 v136, v252
	v_mov_b32_e32 v137, v253
	s_nop 0
	v_mov_b32_e32 v130, v150
	v_mov_b32_e32 v131, v151
	v_mov_b32_e32 v132, v152
	v_mov_b32_e32 v133, v153
	s_andn2_b64 vcc, exec, s[2:3]
	s_mov_b64 s[0:1], -1
	s_waitcnt vmcnt(8)
	v_lshlrev_b32_e32 v165, 16, v166
	v_and_b32_e32 v190, 0xffff0000, v166
	v_lshlrev_b32_e32 v191, 16, v167
	v_lshlrev_b32_e32 v193, 16, v168
	v_and_b32_e32 v194, 0xffff0000, v168
	v_lshlrev_b32_e32 v195, 16, v169
	v_and_b32_e32 v196, 0xffff0000, v169
	v_and_b32_e32 v192, 0xffff0000, v167
	v_mul_f32_e32 v165, 0xbfb8aa3b, v165
	v_mul_f32_e32 v193, 0xbfb8aa3b, v193
	v_mul_f32_e32 v190, 0xbfb8aa3b, v190
	v_mul_f32_e32 v194, 0xbfb8aa3b, v194
	v_mul_f32_e32 v191, 0xbfb8aa3b, v191
	v_mul_f32_e32 v195, 0xbfb8aa3b, v195
	v_mul_f32_e32 v196, 0xbfb8aa3b, v196
	v_mul_f32_e32 v192, 0xbfb8aa3b, v192
	v_lshlrev_b32_e32 v202, 16, v176
	v_and_b32_e32 v203, 0xffff0000, v176
	v_lshlrev_b32_e32 v204, 16, v177
	v_and_b32_e32 v205, 0xffff0000, v177
	v_lshlrev_b32_e32 v176, 16, v179
	v_and_b32_e32 v177, 0xffff0000, v179
	v_exp_f32_e32 v165, v165
	v_exp_f32_e32 v179, v193
	v_exp_f32_e32 v190, v190
	v_exp_f32_e32 v193, v194
	v_exp_f32_e32 v191, v191
	v_exp_f32_e32 v194, v195
	v_exp_f32_e32 v195, v196
	v_exp_f32_e32 v192, v192
	v_add_f32_e32 v165, 1.0, v165
	v_add_f32_e32 v179, 1.0, v179
	v_add_f32_e32 v196, 1.0, v190
	v_add_f32_e32 v193, 1.0, v193
	v_add_f32_e32 v197, 1.0, v191
	v_add_f32_e32 v206, 1.0, v194
	v_add_f32_e32 v208, 1.0, v195
	v_add_f32_e32 v207, 1.0, v192
	v_rcp_f32_e32 v190, v165
	v_rcp_f32_e32 v192, v179
	v_rcp_f32_e32 v191, v196
	v_rcp_f32_e32 v194, v197
	v_rcp_f32_e32 v196, v206
	v_rcp_f32_e32 v197, v208
	v_rcp_f32_e32 v193, v193
	v_rcp_f32_e32 v195, v207
	v_lshlrev_b32_e32 v166, 16, v170
	v_and_b32_e32 v167, 0xffff0000, v170
	v_lshlrev_b32_e32 v168, 16, v171
	v_and_b32_e32 v169, 0xffff0000, v171
	v_lshlrev_b32_e32 v170, 16, v172
	v_and_b32_e32 v171, 0xffff0000, v172
	v_lshlrev_b32_e32 v172, 16, v173
	v_and_b32_e32 v173, 0xffff0000, v173
	v_lshlrev_b32_e32 v200, 16, v175
	v_pk_fma_f32 v[126:127], v[126:127], v[190:191], v[166:167]
	v_pk_fma_f32 v[166:167], v[124:125], v[196:197], v[172:173]
	v_pk_fma_f32 v[124:125], v[122:123], v[192:193], v[170:171]
	v_pk_fma_f32 v[128:129], v[128:129], v[194:195], v[168:169]
	v_cvt_pk_bf16_f32 v124, v124, v125
	v_cvt_pk_bf16_f32 v125, v166, v167
	v_mul_f32_e32 v167, 0xbfb8aa3b, v200
	v_and_b32_e32 v199, 0xffff0000, v174
	v_cvt_pk_bf16_f32 v123, v128, v129
	v_mul_f32_e32 v129, 0xbfb8aa3b, v202
	v_exp_f32_e32 v167, v167
	v_mul_f32_e32 v168, 0xbfb8aa3b, v204
	v_exp_f32_e32 v129, v129
	v_mul_f32_e32 v165, 0xbfb8aa3b, v199
	v_exp_f32_e32 v169, v168
	v_exp_f32_e32 v165, v165
	v_and_b32_e32 v201, 0xffff0000, v175
	v_add_f32_e32 v167, 1.0, v167
	v_add_f32_e32 v129, 1.0, v129
	v_rcp_f32_e32 v168, v167
	v_add_f32_e32 v167, 1.0, v169
	v_mul_f32_e32 v169, 0xbfb8aa3b, v201
	v_rcp_f32_e32 v166, v129
	v_add_f32_e32 v129, 1.0, v165
	v_mul_f32_e32 v165, 0xbfb8aa3b, v203
	v_exp_f32_e32 v169, v169
	v_mul_f32_e32 v170, 0xbfb8aa3b, v205
	v_exp_f32_e32 v165, v165
	v_exp_f32_e32 v171, v170
	v_rcp_f32_e32 v170, v167
	v_add_f32_e32 v167, 1.0, v169
	v_add_f32_e32 v165, 1.0, v165
	v_rcp_f32_e32 v169, v167
	v_add_f32_e32 v167, 1.0, v171
	v_rcp_f32_e32 v171, v167
	v_rcp_f32_e32 v167, v165
	v_lshlrev_b32_e32 v198, 16, v174
	v_cvt_pk_bf16_f32 v122, v126, v127
	v_mul_f32_e32 v126, 0xbfb8aa3b, v198
	v_lshlrev_b32_e32 v174, 16, v178
	v_and_b32_e32 v175, 0xffff0000, v178
	v_lshlrev_b32_e32 v178, 16, v180
	v_exp_f32_e32 v128, v126
	v_and_b32_e32 v179, 0xffff0000, v180
	v_lshlrev_b32_e32 v126, 16, v181
	v_and_b32_e32 v127, 0xffff0000, v181
	v_pk_fma_f32 v[126:127], v[116:117], v[170:171], v[126:127]
	v_pk_fma_f32 v[116:117], v[114:115], v[166:167], v[178:179]
	v_and_b32_e32 v165, 0xffff0000, v182
	v_cvt_pk_bf16_f32 v116, v116, v117
	v_cvt_pk_bf16_f32 v117, v126, v127
	v_lshlrev_b32_e32 v127, 16, v182
	v_lshlrev_b32_e32 v166, 16, v184
	v_mul_f32_e32 v127, 0xbfb8aa3b, v127
	v_exp_f32_e32 v167, v127
	v_mul_f32_e32 v166, 0xbfb8aa3b, v166
	v_mul_f32_e32 v165, 0xbfb8aa3b, v165
	v_pk_fma_f32 v[120:121], v[120:121], v[168:169], v[176:177]
	v_exp_f32_e32 v168, v166
	v_exp_f32_e32 v165, v165
	v_lshlrev_b32_e32 v169, 16, v183
	v_add_f32_e32 v167, 1.0, v167
	v_and_b32_e32 v170, 0xffff0000, v184
	v_lshlrev_b32_e32 v172, 16, v185
	v_rcp_f32_e32 v166, v167
	v_add_f32_e32 v167, 1.0, v168
	v_add_f32_e32 v165, 1.0, v165
	v_mul_f32_e32 v169, 0xbfb8aa3b, v169
	v_rcp_f32_e32 v168, v167
	v_rcp_f32_e32 v167, v165
	v_mul_f32_e32 v165, 0xbfb8aa3b, v170
	v_exp_f32_e32 v169, v169
	v_mul_f32_e32 v170, 0xbfb8aa3b, v172
	v_exp_f32_e32 v172, v170
	v_and_b32_e32 v171, 0xffff0000, v183
	v_and_b32_e32 v173, 0xffff0000, v185
	v_add_f32_e32 v169, 1.0, v169
	v_mul_f32_e32 v171, 0xbfb8aa3b, v171
	v_rcp_f32_e32 v170, v169
	v_add_f32_e32 v169, 1.0, v172
	v_exp_f32_e32 v171, v171
	v_mul_f32_e32 v172, 0xbfb8aa3b, v173
	v_exp_f32_e32 v173, v172
	v_exp_f32_e32 v165, v165
	v_add_f32_e32 v128, 1.0, v128
	v_rcp_f32_e32 v172, v169
	v_add_f32_e32 v169, 1.0, v171
	v_rcp_f32_e32 v128, v128
	v_rcp_f32_e32 v129, v129
	v_rcp_f32_e32 v171, v169
	v_add_f32_e32 v169, 1.0, v173
	v_rcp_f32_e32 v173, v169
	v_add_f32_e32 v165, 1.0, v165
	v_rcp_f32_e32 v169, v165
	v_pk_fma_f32 v[118:119], v[118:119], v[128:129], v[174:175]
	v_lshlrev_b32_e32 v128, 16, v189
	v_and_b32_e32 v129, 0xffff0000, v189
	v_cvt_pk_bf16_f32 v115, v120, v121
	v_lshlrev_b32_e32 v120, 16, v187
	v_and_b32_e32 v121, 0xffff0000, v187
	v_pk_fma_f32 v[108:109], v[108:109], v[172:173], v[128:129]
	v_lshlrev_b32_e32 v126, 16, v188
	v_and_b32_e32 v127, 0xffff0000, v188
	v_pk_fma_f32 v[112:113], v[112:113], v[170:171], v[120:121]
	v_cvt_pk_bf16_f32 v121, v108, v109
	v_or_b32_e32 v108, 32, v156
	v_pk_fma_f32 v[106:107], v[106:107], v[168:169], v[126:127]
	v_ashrrev_i32_e32 v109, 31, v108
	v_cvt_pk_bf16_f32 v120, v106, v107
	v_lshlrev_b64 v[106:107], 10, v[108:109]
	v_cvt_pk_bf16_f32 v114, v118, v119
	v_lshlrev_b32_e32 v118, 16, v186
	v_and_b32_e32 v119, 0xffff0000, v186
	v_lshl_add_u64 v[106:107], v[106:107], 0, v[154:155]
	v_pk_fma_f32 v[110:111], v[110:111], v[166:167], v[118:119]
	v_lshlrev_b64 v[106:107], 1, v[106:107]
	v_cvt_pk_bf16_f32 v118, v110, v111
	v_or_b32_e32 v110, 0x100, v106
	v_mov_b32_e32 v111, v107
	v_cvt_pk_bf16_f32 v119, v112, v113
	v_lshl_add_u64 v[112:113], s[8:9], 0, v[110:111]
	v_lshlrev_b32_e32 v165, 16, v134
	v_and_b32_e32 v174, 0xffff0000, v134
	v_lshlrev_b32_e32 v175, 16, v135
	v_and_b32_e32 v177, 0xffff0000, v135
	v_lshl_add_u64 v[134:135], s[8:9], 0, v[106:107]
	global_load_dwordx4 v[126:129], v[112:113], off
	global_load_dwordx4 v[166:169], v[134:135], off
	v_lshl_add_u64 v[110:111], s[10:11], 0, v[110:111]
	v_lshl_add_u64 v[106:107], s[10:11], 0, v[106:107]
	v_lshlrev_b32_e32 v176, 16, v136
	v_and_b32_e32 v178, 0xffff0000, v136
	v_lshlrev_b32_e32 v179, 16, v137
	v_and_b32_e32 v180, 0xffff0000, v137
	global_load_dwordx4 v[134:137], v[110:111], off
	global_load_dwordx4 v[170:173], v[106:107], off
	v_mul_f32_e32 v107, 0xbfb8aa3b, v165
	v_exp_f32_e32 v165, v107
	v_lshlrev_b32_e32 v110, 16, v133
	v_and_b32_e32 v111, 0xffff0000, v133
	v_mul_f32_e32 v133, 0xbfb8aa3b, v176
	v_lshlrev_b32_e32 v106, 16, v132
	v_and_b32_e32 v107, 0xffff0000, v132
	v_add_f32_e32 v132, 1.0, v165
	v_exp_f32_e32 v133, v133
	v_mul_f32_e32 v165, 0xbfb8aa3b, v174
	v_exp_f32_e32 v165, v165
	v_mul_f32_e32 v175, 0xbfb8aa3b, v175
	v_add_f32_e32 v133, 1.0, v133
	v_exp_f32_e32 v175, v175
	v_mul_f32_e32 v176, 0xbfb8aa3b, v179
	v_rcp_f32_e32 v174, v133
	v_add_f32_e32 v133, 1.0, v165
	v_mul_f32_e32 v165, 0xbfb8aa3b, v178
	v_exp_f32_e32 v178, v176
	v_add_f32_e32 v175, 1.0, v175
	v_mul_f32_e32 v177, 0xbfb8aa3b, v177
	v_rcp_f32_e32 v176, v175
	v_add_f32_e32 v175, 1.0, v178
	v_exp_f32_e32 v177, v177
	v_mul_f32_e32 v178, 0xbfb8aa3b, v180
	v_exp_f32_e32 v179, v178
	v_exp_f32_e32 v165, v165
	v_rcp_f32_e32 v178, v175
	v_add_f32_e32 v175, 1.0, v177
	v_rcp_f32_e32 v177, v175
	v_add_f32_e32 v175, 1.0, v179
	v_add_f32_e32 v165, 1.0, v165
	v_rcp_f32_e32 v179, v175
	v_rcp_f32_e32 v175, v165
	v_rcp_f32_e32 v132, v132
	v_rcp_f32_e32 v133, v133
	v_pk_fma_f32 v[100:101], v[100:101], v[178:179], v[110:111]
	v_or_b32_e32 v110, 48, v156
	v_lshlrev_b32_e32 v112, 16, v130
	v_and_b32_e32 v113, 0xffff0000, v130
	v_pk_fma_f32 v[98:99], v[98:99], v[174:175], v[106:107]
	v_ashrrev_i32_e32 v111, 31, v110
	v_pk_fma_f32 v[102:103], v[102:103], v[132:133], v[112:113]
	v_cvt_pk_bf16_f32 v132, v98, v99
	v_lshlrev_b64 v[98:99], 10, v[110:111]
	v_lshl_add_u64 v[98:99], v[98:99], 0, v[154:155]
	v_lshlrev_b64 v[98:99], 1, v[98:99]
	v_lshlrev_b32_e32 v130, 16, v131
	v_and_b32_e32 v131, 0xffff0000, v131
	v_cvt_pk_bf16_f32 v133, v100, v101
	v_or_b32_e32 v100, 0x100, v98
	v_mov_b32_e32 v101, v99
	v_pk_fma_f32 v[104:105], v[104:105], v[176:177], v[130:131]
	v_cvt_pk_bf16_f32 v130, v102, v103
	v_lshl_add_u64 v[102:103], s[8:9], 0, v[100:101]
	v_cvt_pk_bf16_f32 v131, v104, v105
	v_lshl_add_u64 v[106:107], s[8:9], 0, v[98:99]
	global_load_dwordx4 v[102:105], v[102:103], off
	s_nop 0
	global_load_dwordx4 v[174:177], v[106:107], off
	v_lshl_add_u64 v[100:101], s[10:11], 0, v[100:101]
	v_lshl_add_u64 v[106:107], s[10:11], 0, v[98:99]
	global_load_dwordx4 v[98:101], v[100:101], off
	s_nop 0
	global_load_dwordx4 v[178:181], v[106:107], off
	v_lshlrev_b64 v[106:107], 11, v[156:157]
	v_lshl_add_u64 v[112:113], s[12:13], 0, v[106:107]
	v_lshlrev_b64 v[106:107], 1, v[154:155]
	v_lshl_add_u64 v[112:113], v[112:113], 0, v[106:107]
	global_store_dwordx4 v[112:113], v[122:125], off
	global_store_dwordx4 v[112:113], v[114:117], off offset:256
	v_lshlrev_b64 v[112:113], 11, v[158:159]
	v_lshl_add_u64 v[112:113], s[12:13], 0, v[112:113]
	v_lshl_add_u64 v[112:113], v[112:113], 0, v[106:107]
	global_store_dwordx4 v[112:113], v[118:121], off
	global_store_dwordx4 v[112:113], v[130:133], off offset:256
	v_lshlrev_b64 v[108:109], 11, v[108:109]
	v_lshl_add_u64 v[108:109], s[12:13], 0, v[108:109]
	s_waitcnt vmcnt(10)
	v_lshlrev_b32_e32 v117, 16, v166
	v_lshlrev_b32_e32 v123, 16, v167
	v_lshlrev_b32_e32 v121, 16, v168
	v_and_b32_e32 v120, 0xffff0000, v166
	v_and_b32_e32 v124, 0xffff0000, v168
	v_lshlrev_b32_e32 v130, 16, v169
	v_mul_f32_e32 v117, 0xbfb8aa3b, v117
	v_mul_f32_e32 v121, 0xbfb8aa3b, v121
	v_mul_f32_e32 v123, 0xbfb8aa3b, v123
	v_exp_f32_e32 v122, v117
	v_exp_f32_e32 v121, v121
	v_mul_f32_e32 v120, 0xbfb8aa3b, v120
	v_mul_f32_e32 v124, 0xbfb8aa3b, v124
	v_exp_f32_e32 v123, v123
	v_mul_f32_e32 v130, 0xbfb8aa3b, v130
	v_exp_f32_e32 v132, v120
	v_exp_f32_e32 v124, v124
	v_exp_f32_e32 v130, v130
	v_and_b32_e32 v125, 0xffff0000, v167
	v_and_b32_e32 v131, 0xffff0000, v169
	v_add_f32_e32 v122, 1.0, v122
	v_add_f32_e32 v121, 1.0, v121
	v_add_f32_e32 v123, 1.0, v123
	v_mul_f32_e32 v125, 0xbfb8aa3b, v125
	v_rcp_f32_e32 v120, v122
	v_rcp_f32_e32 v122, v121
	v_add_f32_e32 v121, 1.0, v132
	v_add_f32_e32 v132, 1.0, v124
	v_rcp_f32_e32 v124, v123
	v_add_f32_e32 v123, 1.0, v130
	v_exp_f32_e32 v125, v125
	v_mul_f32_e32 v130, 0xbfb8aa3b, v131
	v_exp_f32_e32 v131, v130
	v_rcp_f32_e32 v130, v123
	v_add_f32_e32 v123, 1.0, v125
	v_rcp_f32_e32 v125, v123
	v_add_f32_e32 v123, 1.0, v131
	v_rcp_f32_e32 v121, v121
	v_rcp_f32_e32 v131, v123
	v_rcp_f32_e32 v123, v132
	s_waitcnt vmcnt(8)
	v_lshlrev_b32_e32 v112, 16, v170
	v_and_b32_e32 v113, 0xffff0000, v170
	v_lshlrev_b32_e32 v116, 16, v172
	v_and_b32_e32 v117, 0xffff0000, v172
	v_lshlrev_b32_e32 v118, 16, v173
	v_and_b32_e32 v119, 0xffff0000, v173
	v_pk_fma_f32 v[94:95], v[94:95], v[120:121], v[112:113]
	v_pk_fma_f32 v[112:113], v[92:93], v[130:131], v[118:119]
	v_pk_fma_f32 v[92:93], v[90:91], v[122:123], v[116:117]
	v_lshlrev_b32_e32 v119, 16, v127
	v_cvt_pk_bf16_f32 v92, v92, v93
	v_cvt_pk_bf16_f32 v93, v112, v113
	v_lshlrev_b32_e32 v113, 16, v126
	v_lshlrev_b32_e32 v117, 16, v128
	v_and_b32_e32 v116, 0xffff0000, v126
	v_and_b32_e32 v120, 0xffff0000, v128
	v_lshlrev_b32_e32 v122, 16, v129
	v_mul_f32_e32 v113, 0xbfb8aa3b, v113
	v_mul_f32_e32 v117, 0xbfb8aa3b, v117
	v_mul_f32_e32 v119, 0xbfb8aa3b, v119
	v_lshlrev_b32_e32 v114, 16, v171
	v_and_b32_e32 v115, 0xffff0000, v171
	v_exp_f32_e32 v118, v113
	v_exp_f32_e32 v117, v117
	v_mul_f32_e32 v116, 0xbfb8aa3b, v116
	v_mul_f32_e32 v120, 0xbfb8aa3b, v120
	v_exp_f32_e32 v119, v119
	v_mul_f32_e32 v122, 0xbfb8aa3b, v122
	v_pk_fma_f32 v[96:97], v[96:97], v[124:125], v[114:115]
	v_exp_f32_e32 v124, v116
	v_exp_f32_e32 v120, v120
	v_exp_f32_e32 v122, v122
	v_and_b32_e32 v121, 0xffff0000, v127
	v_and_b32_e32 v123, 0xffff0000, v129
	v_add_f32_e32 v118, 1.0, v118
	v_add_f32_e32 v117, 1.0, v117
	v_add_f32_e32 v119, 1.0, v119
	v_mul_f32_e32 v121, 0xbfb8aa3b, v121
	v_rcp_f32_e32 v116, v118
	v_rcp_f32_e32 v118, v117
	v_add_f32_e32 v117, 1.0, v124
	v_add_f32_e32 v124, 1.0, v120
	v_rcp_f32_e32 v120, v119
	v_add_f32_e32 v119, 1.0, v122
	v_exp_f32_e32 v121, v121
	v_mul_f32_e32 v122, 0xbfb8aa3b, v123
	v_exp_f32_e32 v123, v122
	v_rcp_f32_e32 v122, v119
	v_add_f32_e32 v119, 1.0, v121
	v_rcp_f32_e32 v121, v119
	v_add_f32_e32 v119, 1.0, v123
	v_rcp_f32_e32 v117, v117
	v_rcp_f32_e32 v123, v119
	v_rcp_f32_e32 v119, v124
	v_cvt_pk_bf16_f32 v90, v94, v95
	v_lshlrev_b32_e32 v94, 16, v134
	v_and_b32_e32 v95, 0xffff0000, v134
	v_lshlrev_b32_e32 v112, 16, v136
	v_and_b32_e32 v113, 0xffff0000, v136
	v_lshlrev_b32_e32 v114, 16, v137
	v_and_b32_e32 v115, 0xffff0000, v137
	v_pk_fma_f32 v[86:87], v[86:87], v[116:117], v[94:95]
	v_pk_fma_f32 v[94:95], v[84:85], v[122:123], v[114:115]
	v_pk_fma_f32 v[84:85], v[82:83], v[118:119], v[112:113]
	s_waitcnt vmcnt(6)
	v_lshlrev_b32_e32 v115, 16, v175
	v_cvt_pk_bf16_f32 v84, v84, v85
	v_cvt_pk_bf16_f32 v85, v94, v95
	v_lshlrev_b32_e32 v95, 16, v174
	v_lshlrev_b32_e32 v113, 16, v176
	v_and_b32_e32 v112, 0xffff0000, v174
	v_and_b32_e32 v116, 0xffff0000, v176
	v_lshlrev_b32_e32 v118, 16, v177
	v_mul_f32_e32 v95, 0xbfb8aa3b, v95
	v_mul_f32_e32 v113, 0xbfb8aa3b, v113
	v_mul_f32_e32 v115, 0xbfb8aa3b, v115
	v_cvt_pk_bf16_f32 v91, v96, v97
	v_lshlrev_b32_e32 v96, 16, v135
	v_and_b32_e32 v97, 0xffff0000, v135
	v_exp_f32_e32 v114, v95
	v_exp_f32_e32 v113, v113
	v_mul_f32_e32 v112, 0xbfb8aa3b, v112
	v_mul_f32_e32 v116, 0xbfb8aa3b, v116
	v_exp_f32_e32 v115, v115
	v_mul_f32_e32 v118, 0xbfb8aa3b, v118
	v_pk_fma_f32 v[88:89], v[88:89], v[120:121], v[96:97]
	v_exp_f32_e32 v120, v112
	v_exp_f32_e32 v116, v116
	v_exp_f32_e32 v118, v118
	v_and_b32_e32 v117, 0xffff0000, v175
	v_and_b32_e32 v119, 0xffff0000, v177
	v_add_f32_e32 v114, 1.0, v114
	v_add_f32_e32 v113, 1.0, v113
	v_add_f32_e32 v115, 1.0, v115
	v_mul_f32_e32 v117, 0xbfb8aa3b, v117
	v_rcp_f32_e32 v112, v114
	v_rcp_f32_e32 v114, v113
	v_add_f32_e32 v113, 1.0, v120
	v_add_f32_e32 v120, 1.0, v116
	v_rcp_f32_e32 v116, v115
	v_add_f32_e32 v115, 1.0, v118
	v_exp_f32_e32 v117, v117
	v_mul_f32_e32 v118, 0xbfb8aa3b, v119
	v_exp_f32_e32 v119, v118
	v_rcp_f32_e32 v118, v115
	v_add_f32_e32 v115, 1.0, v117
	v_rcp_f32_e32 v117, v115
	v_add_f32_e32 v115, 1.0, v119
	v_rcp_f32_e32 v113, v113
	v_rcp_f32_e32 v119, v115
	v_rcp_f32_e32 v115, v120
	v_cvt_pk_bf16_f32 v82, v86, v87
	v_cvt_pk_bf16_f32 v83, v88, v89
	s_waitcnt vmcnt(4)
	v_lshlrev_b32_e32 v86, 16, v178
	v_and_b32_e32 v87, 0xffff0000, v178
	v_lshlrev_b32_e32 v88, 16, v179
	v_and_b32_e32 v89, 0xffff0000, v179
	v_lshlrev_b32_e32 v94, 16, v180
	v_and_b32_e32 v95, 0xffff0000, v180
	v_pk_fma_f32 v[80:81], v[80:81], v[116:117], v[88:89]
	v_pk_fma_f32 v[78:79], v[78:79], v[112:113], v[86:87]
	v_pk_fma_f32 v[74:75], v[74:75], v[114:115], v[94:95]
	v_lshlrev_b32_e32 v96, 16, v181
	v_and_b32_e32 v97, 0xffff0000, v181
	v_cvt_pk_bf16_f32 v78, v78, v79
	v_cvt_pk_bf16_f32 v79, v80, v81
	v_cvt_pk_bf16_f32 v80, v74, v75
	v_add_u32_e32 v74, 0x80, v156
	v_pk_fma_f32 v[76:77], v[76:77], v[118:119], v[96:97]
	v_ashrrev_i32_e32 v75, 31, v74
	v_cvt_pk_bf16_f32 v81, v76, v77
	v_lshlrev_b64 v[76:77], 10, v[74:75]
	v_lshl_add_u64 v[76:77], v[76:77], 0, v[154:155]
	v_lshlrev_b64 v[76:77], 1, v[76:77]
	v_lshlrev_b32_e32 v118, 16, v102
	v_and_b32_e32 v119, 0xffff0000, v102
	v_lshlrev_b32_e32 v121, 16, v103
	v_and_b32_e32 v123, 0xffff0000, v103
	v_or_b32_e32 v102, 0x100, v76
	v_mov_b32_e32 v103, v77
	v_lshl_add_u64 v[86:87], s[8:9], 0, v[102:103]
	v_lshl_add_u64 v[94:95], s[8:9], 0, v[76:77]
	global_load_dwordx4 v[86:89], v[86:87], off
	s_nop 0
	global_load_dwordx4 v[94:97], v[94:95], off
	v_and_b32_e32 v122, 0xffff0000, v104
	v_lshlrev_b32_e32 v124, 16, v105
	v_mul_f32_e32 v121, 0xbfb8aa3b, v121
	v_lshl_add_u64 v[102:103], s[10:11], 0, v[102:103]
	v_mul_f32_e32 v122, 0xbfb8aa3b, v122
	v_exp_f32_e32 v121, v121
	v_mul_f32_e32 v124, 0xbfb8aa3b, v124
	v_lshlrev_b32_e32 v120, 16, v104
	v_and_b32_e32 v125, 0xffff0000, v105
	v_lshl_add_u64 v[76:77], s[10:11], 0, v[76:77]
	global_load_dwordx4 v[102:105], v[102:103], off
	s_nop 0
	global_load_dwordx4 v[112:115], v[76:77], off
	v_exp_f32_e32 v122, v122
	v_exp_f32_e32 v124, v124
	v_add_f32_e32 v121, 1.0, v121
	v_mul_f32_e32 v123, 0xbfb8aa3b, v123
	v_mul_f32_e32 v120, 0xbfb8aa3b, v120
	v_add_f32_e32 v126, 1.0, v122
	v_rcp_f32_e32 v122, v121
	v_add_f32_e32 v121, 1.0, v124
	v_exp_f32_e32 v123, v123
	v_mul_f32_e32 v124, 0xbfb8aa3b, v125
	v_exp_f32_e32 v120, v120
	v_exp_f32_e32 v125, v124
	v_lshlrev_b32_e32 v76, 16, v99
	v_and_b32_e32 v77, 0xffff0000, v99
	v_mul_f32_e32 v99, 0xbfb8aa3b, v118
	v_mul_f32_e32 v119, 0xbfb8aa3b, v119
	v_rcp_f32_e32 v124, v121
	v_add_f32_e32 v121, 1.0, v123
	v_exp_f32_e32 v118, v99
	v_exp_f32_e32 v119, v119
	v_add_f32_e32 v120, 1.0, v120
	v_rcp_f32_e32 v123, v121
	v_add_f32_e32 v121, 1.0, v125
	v_rcp_f32_e32 v120, v120
	v_rcp_f32_e32 v125, v121
	v_rcp_f32_e32 v121, v126
	v_lshlrev_b32_e32 v116, 16, v98
	v_and_b32_e32 v117, 0xffff0000, v98
	v_lshlrev_b32_e32 v98, 16, v100
	v_and_b32_e32 v99, 0xffff0000, v100
	v_add_f32_e32 v118, 1.0, v118
	v_add_f32_e32 v119, 1.0, v119
	v_pk_fma_f32 v[72:73], v[72:73], v[122:123], v[76:77]
	v_add_u32_e32 v76, 0x90, v156
	v_lshlrev_b32_e32 v100, 16, v101
	v_and_b32_e32 v101, 0xffff0000, v101
	v_rcp_f32_e32 v118, v118
	v_rcp_f32_e32 v119, v119
	v_pk_fma_f32 v[66:67], v[66:67], v[120:121], v[98:99]
	v_ashrrev_i32_e32 v77, 31, v76
	v_pk_fma_f32 v[68:69], v[68:69], v[124:125], v[100:101]
	v_cvt_pk_bf16_f32 v100, v66, v67
	v_lshlrev_b64 v[66:67], 10, v[76:77]
	v_lshl_add_u64 v[66:67], v[66:67], 0, v[154:155]
	v_lshlrev_b64 v[66:67], 1, v[66:67]
	v_pk_fma_f32 v[70:71], v[70:71], v[118:119], v[116:117]
	v_cvt_pk_bf16_f32 v101, v68, v69
	v_or_b32_e32 v68, 0x100, v66
	v_mov_b32_e32 v69, v67
	v_cvt_pk_bf16_f32 v98, v70, v71
	v_lshl_add_u64 v[70:71], s[8:9], 0, v[68:69]
	v_lshl_add_u64 v[116:117], s[8:9], 0, v[66:67]
	v_cvt_pk_bf16_f32 v99, v72, v73
	global_load_dwordx4 v[70:73], v[70:71], off
	s_nop 0
	global_load_dwordx4 v[116:119], v[116:117], off
	v_lshl_add_u64 v[68:69], s[10:11], 0, v[68:69]
	v_lshl_add_u64 v[120:121], s[10:11], 0, v[66:67]
	global_load_dwordx4 v[66:69], v[68:69], off
	s_nop 0
	global_load_dwordx4 v[120:123], v[120:121], off
	v_lshl_add_u64 v[108:109], v[108:109], 0, v[106:107]
	global_store_dwordx4 v[108:109], v[90:93], off
	global_store_dwordx4 v[108:109], v[82:85], off offset:256
	v_lshlrev_b64 v[74:75], 11, v[74:75]
	v_lshl_add_u64 v[74:75], s[12:13], 0, v[74:75]
	v_lshlrev_b64 v[82:83], 11, v[110:111]
	v_lshl_add_u64 v[82:83], s[12:13], 0, v[82:83]
	v_lshl_add_u64 v[82:83], v[82:83], 0, v[106:107]
	global_store_dwordx4 v[82:83], v[78:81], off
	global_store_dwordx4 v[82:83], v[98:101], off offset:256
	v_lshl_add_u64 v[74:75], v[74:75], 0, v[106:107]
	s_waitcnt vmcnt(10)
	v_lshlrev_b32_e32 v83, 16, v94
	v_lshlrev_b32_e32 v93, 16, v95
	v_lshlrev_b32_e32 v91, 16, v96
	v_and_b32_e32 v90, 0xffff0000, v94
	v_and_b32_e32 v94, 0xffff0000, v96
	v_lshlrev_b32_e32 v96, 16, v97
	v_mul_f32_e32 v83, 0xbfb8aa3b, v83
	v_mul_f32_e32 v91, 0xbfb8aa3b, v91
	v_mul_f32_e32 v93, 0xbfb8aa3b, v93
	v_exp_f32_e32 v92, v83
	v_exp_f32_e32 v91, v91
	v_mul_f32_e32 v90, 0xbfb8aa3b, v90
	v_mul_f32_e32 v94, 0xbfb8aa3b, v94
	v_exp_f32_e32 v93, v93
	v_mul_f32_e32 v96, 0xbfb8aa3b, v96
	v_exp_f32_e32 v98, v90
	v_exp_f32_e32 v94, v94
	v_exp_f32_e32 v96, v96
	v_and_b32_e32 v95, 0xffff0000, v95
	v_and_b32_e32 v97, 0xffff0000, v97
	v_add_f32_e32 v92, 1.0, v92
	v_add_f32_e32 v91, 1.0, v91
	v_add_f32_e32 v93, 1.0, v93
	v_mul_f32_e32 v95, 0xbfb8aa3b, v95
	v_rcp_f32_e32 v90, v92
	v_rcp_f32_e32 v92, v91
	v_add_f32_e32 v91, 1.0, v98
	v_add_f32_e32 v98, 1.0, v94
	v_rcp_f32_e32 v94, v93
	v_add_f32_e32 v93, 1.0, v96
	v_exp_f32_e32 v95, v95
	v_mul_f32_e32 v96, 0xbfb8aa3b, v97
	v_exp_f32_e32 v97, v96
	v_rcp_f32_e32 v96, v93
	v_add_f32_e32 v93, 1.0, v95
	v_rcp_f32_e32 v95, v93
	v_add_f32_e32 v93, 1.0, v97
	v_rcp_f32_e32 v91, v91
	v_rcp_f32_e32 v97, v93
	v_rcp_f32_e32 v93, v98
	s_waitcnt vmcnt(8)
	v_lshlrev_b32_e32 v78, 16, v112
	v_and_b32_e32 v79, 0xffff0000, v112
	v_lshlrev_b32_e32 v82, 16, v114
	v_and_b32_e32 v83, 0xffff0000, v114
	v_lshlrev_b32_e32 v84, 16, v115
	v_and_b32_e32 v85, 0xffff0000, v115
	v_pk_fma_f32 v[62:63], v[62:63], v[90:91], v[78:79]
	v_pk_fma_f32 v[78:79], v[60:61], v[96:97], v[84:85]
	v_pk_fma_f32 v[60:61], v[58:59], v[92:93], v[82:83]
	v_lshlrev_b32_e32 v85, 16, v87
	v_cvt_pk_bf16_f32 v60, v60, v61
	v_cvt_pk_bf16_f32 v61, v78, v79
	v_lshlrev_b32_e32 v79, 16, v86
	v_lshlrev_b32_e32 v83, 16, v88
	v_and_b32_e32 v82, 0xffff0000, v86
	v_and_b32_e32 v86, 0xffff0000, v88
	v_lshlrev_b32_e32 v88, 16, v89
	v_mul_f32_e32 v79, 0xbfb8aa3b, v79
	v_mul_f32_e32 v83, 0xbfb8aa3b, v83
	v_mul_f32_e32 v85, 0xbfb8aa3b, v85
	v_exp_f32_e32 v84, v79
	v_exp_f32_e32 v83, v83
	v_mul_f32_e32 v82, 0xbfb8aa3b, v82
	v_mul_f32_e32 v86, 0xbfb8aa3b, v86
	v_exp_f32_e32 v85, v85
	v_mul_f32_e32 v88, 0xbfb8aa3b, v88
	v_exp_f32_e32 v90, v82
	v_exp_f32_e32 v86, v86
	v_exp_f32_e32 v88, v88
	v_and_b32_e32 v87, 0xffff0000, v87
	v_and_b32_e32 v89, 0xffff0000, v89
	v_add_f32_e32 v84, 1.0, v84
	v_add_f32_e32 v83, 1.0, v83
	v_add_f32_e32 v85, 1.0, v85
	v_mul_f32_e32 v87, 0xbfb8aa3b, v87
	v_rcp_f32_e32 v82, v84
	v_rcp_f32_e32 v84, v83
	v_add_f32_e32 v83, 1.0, v90
	v_add_f32_e32 v90, 1.0, v86
	v_rcp_f32_e32 v86, v85
	v_add_f32_e32 v85, 1.0, v88
	v_exp_f32_e32 v87, v87
	v_mul_f32_e32 v88, 0xbfb8aa3b, v89
	v_exp_f32_e32 v89, v88
	v_rcp_f32_e32 v88, v85
	v_add_f32_e32 v85, 1.0, v87
	v_rcp_f32_e32 v87, v85
	v_add_f32_e32 v85, 1.0, v89
	v_rcp_f32_e32 v83, v83
	v_rcp_f32_e32 v89, v85
	v_rcp_f32_e32 v85, v90
	v_lshlrev_b32_e32 v80, 16, v113
	v_and_b32_e32 v81, 0xffff0000, v113
	v_pk_fma_f32 v[64:65], v[64:65], v[94:95], v[80:81]
	v_cvt_pk_bf16_f32 v58, v62, v63
	v_lshlrev_b32_e32 v62, 16, v102
	v_and_b32_e32 v63, 0xffff0000, v102
	v_lshlrev_b32_e32 v78, 16, v104
	v_and_b32_e32 v79, 0xffff0000, v104
	v_lshlrev_b32_e32 v80, 16, v105
	v_and_b32_e32 v81, 0xffff0000, v105
	v_pk_fma_f32 v[54:55], v[54:55], v[82:83], v[62:63]
	v_pk_fma_f32 v[62:63], v[52:53], v[88:89], v[80:81]
	v_pk_fma_f32 v[52:53], v[50:51], v[84:85], v[78:79]
	s_waitcnt vmcnt(6)
	v_lshlrev_b32_e32 v81, 16, v117
	v_cvt_pk_bf16_f32 v52, v52, v53
	v_cvt_pk_bf16_f32 v53, v62, v63
	v_lshlrev_b32_e32 v63, 16, v116
	v_lshlrev_b32_e32 v79, 16, v118
	v_and_b32_e32 v78, 0xffff0000, v116
	v_and_b32_e32 v82, 0xffff0000, v118
	v_lshlrev_b32_e32 v84, 16, v119
	v_mul_f32_e32 v63, 0xbfb8aa3b, v63
	v_mul_f32_e32 v79, 0xbfb8aa3b, v79
	v_mul_f32_e32 v81, 0xbfb8aa3b, v81
	v_cvt_pk_bf16_f32 v59, v64, v65
	v_lshlrev_b32_e32 v64, 16, v103
	v_and_b32_e32 v65, 0xffff0000, v103
	v_exp_f32_e32 v80, v63
	v_exp_f32_e32 v79, v79
	v_mul_f32_e32 v78, 0xbfb8aa3b, v78
	v_mul_f32_e32 v82, 0xbfb8aa3b, v82
	v_exp_f32_e32 v81, v81
	v_mul_f32_e32 v84, 0xbfb8aa3b, v84
	v_pk_fma_f32 v[56:57], v[56:57], v[86:87], v[64:65]
	v_exp_f32_e32 v86, v78
	v_exp_f32_e32 v82, v82
	v_exp_f32_e32 v84, v84
	v_and_b32_e32 v83, 0xffff0000, v117
	v_and_b32_e32 v85, 0xffff0000, v119
	v_add_f32_e32 v80, 1.0, v80
	v_add_f32_e32 v79, 1.0, v79
	v_add_f32_e32 v81, 1.0, v81
	v_mul_f32_e32 v83, 0xbfb8aa3b, v83
	v_rcp_f32_e32 v78, v80
	v_rcp_f32_e32 v80, v79
	v_add_f32_e32 v79, 1.0, v86
	v_add_f32_e32 v86, 1.0, v82
	v_rcp_f32_e32 v82, v81
	v_add_f32_e32 v81, 1.0, v84
	v_exp_f32_e32 v83, v83
	v_mul_f32_e32 v84, 0xbfb8aa3b, v85
	v_exp_f32_e32 v85, v84
	v_rcp_f32_e32 v84, v81
	v_add_f32_e32 v81, 1.0, v83
	v_rcp_f32_e32 v79, v79
	v_rcp_f32_e32 v83, v81
	v_add_f32_e32 v81, 1.0, v85
	v_rcp_f32_e32 v85, v81
	v_rcp_f32_e32 v81, v86
	v_cvt_pk_bf16_f32 v50, v54, v55
	s_waitcnt vmcnt(4)
	v_lshlrev_b32_e32 v54, 16, v120
	v_and_b32_e32 v55, 0xffff0000, v120
	v_lshlrev_b32_e32 v62, 16, v122
	v_and_b32_e32 v63, 0xffff0000, v122
	v_pk_fma_f32 v[46:47], v[46:47], v[78:79], v[54:55]
	v_add_u32_e32 v54, 0xb0, v156
	v_lshlrev_b32_e32 v64, 16, v123
	v_and_b32_e32 v65, 0xffff0000, v123
	v_pk_fma_f32 v[42:43], v[42:43], v[80:81], v[62:63]
	v_ashrrev_i32_e32 v55, 31, v54
	v_pk_fma_f32 v[44:45], v[44:45], v[84:85], v[64:65]
	v_cvt_pk_bf16_f32 v64, v42, v43
	v_lshlrev_b64 v[42:43], 10, v[54:55]
	v_lshl_add_u64 v[42:43], v[42:43], 0, v[154:155]
	v_cvt_pk_bf16_f32 v62, v46, v47
	v_lshlrev_b64 v[46:47], 1, v[42:43]
	v_or_b32_e32 v42, 0x100, v46
	v_mov_b32_e32 v43, v47
	v_cvt_pk_bf16_f32 v65, v44, v45
	v_lshlrev_b32_e32 v85, 16, v72
	v_lshl_add_u64 v[44:45], s[8:9], 0, v[42:43]
	v_cvt_pk_bf16_f32 v51, v56, v57
	v_lshlrev_b32_e32 v56, 16, v121
	v_and_b32_e32 v57, 0xffff0000, v121
	global_load_dwordx4 v[78:81], v[44:45], off
	v_lshlrev_b32_e32 v44, 16, v66
	v_and_b32_e32 v45, 0xffff0000, v66
	v_mul_f32_e32 v66, 0xbfb8aa3b, v85
	v_pk_fma_f32 v[48:49], v[48:49], v[82:83], v[56:57]
	v_and_b32_e32 v57, 0xffff0000, v70
	v_exp_f32_e32 v66, v66
	v_mul_f32_e32 v57, 0xbfb8aa3b, v57
	v_exp_f32_e32 v57, v57
	v_and_b32_e32 v72, 0xffff0000, v72
	v_add_f32_e32 v66, 1.0, v66
	v_lshl_add_u64 v[42:43], s[10:11], 0, v[42:43]
	v_cvt_pk_bf16_f32 v63, v48, v49
	v_lshlrev_b32_e32 v56, 16, v70
	v_lshlrev_b32_e32 v70, 16, v71
	v_lshlrev_b32_e32 v48, 16, v67
	v_and_b32_e32 v49, 0xffff0000, v67
	v_lshlrev_b32_e32 v82, 16, v68
	v_and_b32_e32 v83, 0xffff0000, v68
	v_lshlrev_b32_e32 v84, 16, v69
	v_and_b32_e32 v85, 0xffff0000, v69
	v_rcp_f32_e32 v86, v66
	global_load_dwordx4 v[66:69], v[42:43], off
	v_mul_f32_e32 v43, 0xbfb8aa3b, v72
	v_add_f32_e32 v42, 1.0, v57
	v_exp_f32_e32 v43, v43
	v_mul_f32_e32 v57, 0xbfb8aa3b, v70
	v_exp_f32_e32 v70, v57
	v_lshlrev_b32_e32 v88, 16, v73
	v_mul_f32_e32 v56, 0xbfb8aa3b, v56
	v_and_b32_e32 v71, 0xffff0000, v71
	v_exp_f32_e32 v56, v56
	v_rcp_f32_e32 v57, v42
	v_add_f32_e32 v42, 1.0, v43
	v_mul_f32_e32 v43, 0xbfb8aa3b, v88
	v_rcp_f32_e32 v87, v42
	v_add_f32_e32 v42, 1.0, v70
	v_exp_f32_e32 v43, v43
	v_mul_f32_e32 v70, 0xbfb8aa3b, v71
	v_exp_f32_e32 v70, v70
	v_and_b32_e32 v73, 0xffff0000, v73
	v_add_f32_e32 v56, 1.0, v56
	v_rcp_f32_e32 v56, v56
	v_add_f32_e32 v71, 1.0, v43
	v_mul_f32_e32 v43, 0xbfb8aa3b, v73
	v_exp_f32_e32 v72, v43
	v_add_f32_e32 v43, 1.0, v70
	v_rcp_f32_e32 v42, v42
	v_rcp_f32_e32 v43, v43
	v_pk_fma_f32 v[38:39], v[38:39], v[56:57], v[44:45]
	v_add_u32_e32 v56, 0xa0, v156
	v_ashrrev_i32_e32 v57, 31, v56
	v_pk_fma_f32 v[40:41], v[40:41], v[42:43], v[48:49]
	v_lshlrev_b64 v[42:43], 10, v[56:57]
	v_lshl_add_u64 v[42:43], v[42:43], 0, v[154:155]
	v_lshlrev_b64 v[48:49], 1, v[42:43]
	v_add_f32_e32 v70, 1.0, v72
	v_or_b32_e32 v90, 0x100, v48
	v_mov_b32_e32 v91, v49
	v_rcp_f32_e32 v88, v71
	v_rcp_f32_e32 v89, v70
	v_lshl_add_u64 v[42:43], s[8:9], 0, v[90:91]
	v_lshl_add_u64 v[70:71], s[8:9], 0, v[46:47]
	global_load_dwordx4 v[42:45], v[42:43], off
	s_nop 0
	global_load_dwordx4 v[70:73], v[70:71], off
	v_pk_fma_f32 v[34:35], v[34:35], v[86:87], v[82:83]
	v_pk_fma_f32 v[36:37], v[36:37], v[88:89], v[84:85]
	v_cvt_pk_bf16_f32 v84, v34, v35
	v_lshl_add_u64 v[34:35], s[8:9], 0, v[48:49]
	v_cvt_pk_bf16_f32 v82, v38, v39
	v_cvt_pk_bf16_f32 v83, v40, v41
	global_load_dwordx4 v[38:41], v[34:35], off
	v_lshl_add_u64 v[34:35], s[10:11], 0, v[46:47]
	global_load_dwordx4 v[86:89], v[34:35], off
	v_cvt_pk_bf16_f32 v85, v36, v37
	v_lshl_add_u64 v[34:35], s[10:11], 0, v[90:91]
	v_lshl_add_u64 v[36:37], s[10:11], 0, v[48:49]
	global_load_dwordx4 v[46:49], v[34:35], off
	s_nop 0
	global_load_dwordx4 v[34:37], v[36:37], off
	s_nop 0
	global_store_dwordx4 v[74:75], v[58:61], off
	global_store_dwordx4 v[74:75], v[50:53], off offset:256
	s_waitcnt vmcnt(8)
	v_lshlrev_b32_e32 v58, 16, v66
	v_lshlrev_b32_e32 v52, 16, v78
	v_and_b32_e32 v53, 0xffff0000, v78
	v_mul_f32_e32 v52, 0xbfb8aa3b, v52
	v_mul_f32_e32 v53, 0xbfb8aa3b, v53
	v_exp_f32_e32 v52, v52
	v_exp_f32_e32 v53, v53
	v_lshlrev_b64 v[50:51], 11, v[76:77]
	v_lshl_add_u64 v[50:51], s[12:13], 0, v[50:51]
	v_lshl_add_u64 v[50:51], v[50:51], 0, v[106:107]
	global_store_dwordx4 v[50:51], v[62:65], off
	global_store_dwordx4 v[50:51], v[82:85], off offset:256
	v_add_f32_e32 v50, 1.0, v52
	v_add_f32_e32 v51, 1.0, v53
	v_rcp_f32_e32 v50, v50
	v_rcp_f32_e32 v51, v51
	v_lshlrev_b32_e32 v52, 16, v79
	v_and_b32_e32 v53, 0xffff0000, v79
	v_mul_f32_e32 v52, 0xbfb8aa3b, v52
	v_mul_f32_e32 v53, 0xbfb8aa3b, v53
	v_exp_f32_e32 v52, v52
	v_exp_f32_e32 v53, v53
	v_and_b32_e32 v59, 0xffff0000, v66
	v_pk_fma_f32 v[30:31], v[30:31], v[50:51], v[58:59]
	v_add_f32_e32 v52, 1.0, v52
	v_cvt_pk_bf16_f32 v30, v30, v31
	v_lshlrev_b32_e32 v31, 16, v80
	v_mul_f32_e32 v31, 0xbfb8aa3b, v31
	v_add_f32_e32 v53, 1.0, v53
	v_exp_f32_e32 v50, v31
	v_and_b32_e32 v31, 0xffff0000, v80
	v_rcp_f32_e32 v52, v52
	v_rcp_f32_e32 v53, v53
	v_mul_f32_e32 v31, 0xbfb8aa3b, v31
	v_exp_f32_e32 v51, v31
	v_lshlrev_b32_e32 v60, 16, v67
	v_and_b32_e32 v61, 0xffff0000, v67
	v_pk_fma_f32 v[32:33], v[32:33], v[52:53], v[60:61]
	v_lshlrev_b32_e32 v52, 16, v68
	v_cvt_pk_bf16_f32 v31, v32, v33
	v_add_f32_e32 v32, 1.0, v50
	v_add_f32_e32 v33, 1.0, v51
	v_rcp_f32_e32 v32, v32
	v_rcp_f32_e32 v33, v33
	v_lshlrev_b32_e32 v50, 16, v81
	v_and_b32_e32 v51, 0xffff0000, v81
	v_mul_f32_e32 v50, 0xbfb8aa3b, v50
	v_mul_f32_e32 v51, 0xbfb8aa3b, v51
	v_exp_f32_e32 v50, v50
	v_exp_f32_e32 v51, v51
	v_and_b32_e32 v53, 0xffff0000, v68
	v_pk_fma_f32 v[26:27], v[26:27], v[32:33], v[52:53]
	v_add_f32_e32 v50, 1.0, v50
	v_cvt_pk_bf16_f32 v32, v26, v27
	s_waitcnt vmcnt(8)
	v_lshlrev_b32_e32 v26, 16, v70
	v_and_b32_e32 v27, 0xffff0000, v70
	v_mul_f32_e32 v26, 0xbfb8aa3b, v26
	v_mul_f32_e32 v27, 0xbfb8aa3b, v27
	v_add_f32_e32 v51, 1.0, v51
	v_exp_f32_e32 v26, v26
	v_exp_f32_e32 v27, v27
	v_rcp_f32_e32 v50, v50
	v_rcp_f32_e32 v51, v51
	v_lshlrev_b32_e32 v58, 16, v69
	v_and_b32_e32 v59, 0xffff0000, v69
	v_add_f32_e32 v26, 1.0, v26
	v_add_f32_e32 v27, 1.0, v27
	v_pk_fma_f32 v[28:29], v[28:29], v[50:51], v[58:59]
	v_rcp_f32_e32 v26, v26
	v_rcp_f32_e32 v27, v27
	v_cvt_pk_bf16_f32 v33, v28, v29
	v_lshlrev_b32_e32 v28, 16, v71
	v_and_b32_e32 v29, 0xffff0000, v71
	v_mul_f32_e32 v28, 0xbfb8aa3b, v28
	v_mul_f32_e32 v29, 0xbfb8aa3b, v29
	v_exp_f32_e32 v28, v28
	v_exp_f32_e32 v29, v29
	s_waitcnt vmcnt(6)
	v_lshlrev_b32_e32 v50, 16, v86
	v_and_b32_e32 v51, 0xffff0000, v86
	v_pk_fma_f32 v[22:23], v[22:23], v[26:27], v[50:51]
	v_add_f32_e32 v28, 1.0, v28
	v_cvt_pk_bf16_f32 v22, v22, v23
	v_lshlrev_b32_e32 v23, 16, v72
	v_mul_f32_e32 v23, 0xbfb8aa3b, v23
	v_add_f32_e32 v29, 1.0, v29
	v_exp_f32_e32 v26, v23
	v_and_b32_e32 v23, 0xffff0000, v72
	v_rcp_f32_e32 v28, v28
	v_rcp_f32_e32 v29, v29
	v_mul_f32_e32 v23, 0xbfb8aa3b, v23
	v_exp_f32_e32 v27, v23
	v_lshlrev_b32_e32 v52, 16, v87
	v_and_b32_e32 v53, 0xffff0000, v87
	v_pk_fma_f32 v[24:25], v[24:25], v[28:29], v[52:53]
	v_lshlrev_b32_e32 v28, 16, v88
	v_cvt_pk_bf16_f32 v23, v24, v25
	v_add_f32_e32 v24, 1.0, v26
	v_add_f32_e32 v25, 1.0, v27
	v_rcp_f32_e32 v24, v24
	v_rcp_f32_e32 v25, v25
	v_lshlrev_b32_e32 v26, 16, v73
	v_and_b32_e32 v27, 0xffff0000, v73
	v_mul_f32_e32 v26, 0xbfb8aa3b, v26
	v_mul_f32_e32 v27, 0xbfb8aa3b, v27
	v_exp_f32_e32 v26, v26
	v_exp_f32_e32 v27, v27
	v_and_b32_e32 v29, 0xffff0000, v88
	v_pk_fma_f32 v[18:19], v[18:19], v[24:25], v[28:29]
	v_add_f32_e32 v26, 1.0, v26
	v_cvt_pk_bf16_f32 v24, v18, v19
	v_lshlrev_b32_e32 v18, 16, v42
	v_and_b32_e32 v19, 0xffff0000, v42
	v_mul_f32_e32 v18, 0xbfb8aa3b, v18
	v_mul_f32_e32 v19, 0xbfb8aa3b, v19
	v_add_f32_e32 v27, 1.0, v27
	v_exp_f32_e32 v18, v18
	v_exp_f32_e32 v19, v19
	v_rcp_f32_e32 v26, v26
	v_rcp_f32_e32 v27, v27
	v_lshlrev_b32_e32 v50, 16, v89
	v_and_b32_e32 v51, 0xffff0000, v89
	v_add_f32_e32 v18, 1.0, v18
	v_add_f32_e32 v19, 1.0, v19
	v_pk_fma_f32 v[20:21], v[20:21], v[26:27], v[50:51]
	v_rcp_f32_e32 v18, v18
	v_rcp_f32_e32 v19, v19
	v_cvt_pk_bf16_f32 v25, v20, v21
	v_lshlrev_b32_e32 v20, 16, v43
	v_and_b32_e32 v21, 0xffff0000, v43
	v_mul_f32_e32 v20, 0xbfb8aa3b, v20
	v_mul_f32_e32 v21, 0xbfb8aa3b, v21
	v_exp_f32_e32 v20, v20
	v_exp_f32_e32 v21, v21
	s_waitcnt vmcnt(5)
	v_lshlrev_b32_e32 v26, 16, v46
	v_and_b32_e32 v27, 0xffff0000, v46
	v_pk_fma_f32 v[14:15], v[14:15], v[18:19], v[26:27]
	v_add_f32_e32 v20, 1.0, v20
	v_cvt_pk_bf16_f32 v14, v14, v15
	v_lshlrev_b32_e32 v15, 16, v44
	v_mul_f32_e32 v15, 0xbfb8aa3b, v15
	v_add_f32_e32 v21, 1.0, v21
	v_exp_f32_e32 v18, v15
	v_and_b32_e32 v15, 0xffff0000, v44
	v_rcp_f32_e32 v20, v20
	v_rcp_f32_e32 v21, v21
	v_mul_f32_e32 v15, 0xbfb8aa3b, v15
	v_exp_f32_e32 v19, v15
	v_lshlrev_b32_e32 v28, 16, v47
	v_and_b32_e32 v29, 0xffff0000, v47
	v_pk_fma_f32 v[16:17], v[16:17], v[20:21], v[28:29]
	v_lshlrev_b32_e32 v20, 16, v48
	v_cvt_pk_bf16_f32 v15, v16, v17
	v_add_f32_e32 v16, 1.0, v18
	v_add_f32_e32 v17, 1.0, v19
	v_rcp_f32_e32 v16, v16
	v_rcp_f32_e32 v17, v17
	v_lshlrev_b32_e32 v18, 16, v45
	v_and_b32_e32 v19, 0xffff0000, v45
	v_mul_f32_e32 v18, 0xbfb8aa3b, v18
	v_mul_f32_e32 v19, 0xbfb8aa3b, v19
	v_exp_f32_e32 v18, v18
	v_exp_f32_e32 v19, v19
	v_and_b32_e32 v21, 0xffff0000, v48
	v_pk_fma_f32 v[10:11], v[10:11], v[16:17], v[20:21]
	v_add_f32_e32 v18, 1.0, v18
	v_cvt_pk_bf16_f32 v16, v10, v11
	v_lshlrev_b32_e32 v10, 16, v38
	v_and_b32_e32 v11, 0xffff0000, v38
	v_mul_f32_e32 v10, 0xbfb8aa3b, v10
	v_mul_f32_e32 v11, 0xbfb8aa3b, v11
	v_add_f32_e32 v19, 1.0, v19
	v_exp_f32_e32 v10, v10
	v_exp_f32_e32 v11, v11
	v_rcp_f32_e32 v18, v18
	v_rcp_f32_e32 v19, v19
	v_lshlrev_b32_e32 v26, 16, v49
	v_and_b32_e32 v27, 0xffff0000, v49
	v_add_f32_e32 v10, 1.0, v10
	v_add_f32_e32 v11, 1.0, v11
	v_pk_fma_f32 v[12:13], v[12:13], v[18:19], v[26:27]
	v_rcp_f32_e32 v10, v10
	v_rcp_f32_e32 v11, v11
	v_cvt_pk_bf16_f32 v17, v12, v13
	v_lshlrev_b32_e32 v12, 16, v39
	v_and_b32_e32 v13, 0xffff0000, v39
	v_mul_f32_e32 v12, 0xbfb8aa3b, v12
	v_mul_f32_e32 v13, 0xbfb8aa3b, v13
	v_exp_f32_e32 v12, v12
	v_exp_f32_e32 v13, v13
	s_waitcnt vmcnt(4)
	v_lshlrev_b32_e32 v18, 16, v34
	v_and_b32_e32 v19, 0xffff0000, v34
	v_pk_fma_f32 v[6:7], v[6:7], v[10:11], v[18:19]
	v_add_f32_e32 v12, 1.0, v12
	v_cvt_pk_bf16_f32 v6, v6, v7
	v_lshlrev_b32_e32 v7, 16, v40
	v_mul_f32_e32 v7, 0xbfb8aa3b, v7
	v_add_f32_e32 v13, 1.0, v13
	v_exp_f32_e32 v10, v7
	v_and_b32_e32 v7, 0xffff0000, v40
	v_rcp_f32_e32 v12, v12
	v_rcp_f32_e32 v13, v13
	v_mul_f32_e32 v7, 0xbfb8aa3b, v7
	v_exp_f32_e32 v11, v7
	v_lshlrev_b32_e32 v20, 16, v35
	v_and_b32_e32 v21, 0xffff0000, v35
	v_pk_fma_f32 v[8:9], v[8:9], v[12:13], v[20:21]
	v_lshlrev_b32_e32 v12, 16, v36
	v_cvt_pk_bf16_f32 v7, v8, v9
	v_add_f32_e32 v8, 1.0, v10
	v_add_f32_e32 v9, 1.0, v11
	v_lshlrev_b32_e32 v10, 16, v41
	v_and_b32_e32 v11, 0xffff0000, v41
	v_mul_f32_e32 v10, 0xbfb8aa3b, v10
	v_mul_f32_e32 v11, 0xbfb8aa3b, v11
	v_exp_f32_e32 v10, v10
	v_exp_f32_e32 v11, v11
	v_rcp_f32_e32 v8, v8
	v_rcp_f32_e32 v9, v9
	v_add_f32_e32 v10, 1.0, v10
	v_add_f32_e32 v11, 1.0, v11
	v_rcp_f32_e32 v10, v10
	v_rcp_f32_e32 v11, v11
	v_and_b32_e32 v13, 0xffff0000, v36
	v_pk_fma_f32 v[2:3], v[2:3], v[8:9], v[12:13]
	v_lshlrev_b32_e32 v18, 16, v37
	v_and_b32_e32 v19, 0xffff0000, v37
	v_cvt_pk_bf16_f32 v8, v2, v3
	v_lshlrev_b64 v[2:3], 11, v[56:57]
	v_pk_fma_f32 v[4:5], v[4:5], v[10:11], v[18:19]
	v_lshl_add_u64 v[2:3], s[12:13], 0, v[2:3]
	v_cvt_pk_bf16_f32 v9, v4, v5
	v_lshl_add_u64 v[2:3], v[2:3], 0, v[106:107]
	global_store_dwordx4 v[2:3], v[6:9], off
	global_store_dwordx4 v[2:3], v[14:17], off offset:256
	v_lshlrev_b64 v[2:3], 11, v[54:55]
	v_lshl_add_u64 v[2:3], s[12:13], 0, v[2:3]
	v_lshl_add_u64 v[2:3], v[2:3], 0, v[106:107]
	global_store_dwordx4 v[2:3], v[22:25], off
	global_store_dwordx4 v[2:3], v[30:33], off offset:256
	s_cbranch_vccnz .LBB0_788
	s_andn2_b64 vcc, exec, s[6:7]
	s_cbranch_vccnz .LBB0_787
	s_barrier
	s_branch .LBB0_787
